# pool pre-pass item: the 9-23 serial row loads (load, vmcnt(0), use) go to a 6-deep register ring with counted waits (all 4 window variants); on top of v132
# speedup vs baseline: 1.0070x; 1.0039x over previous
.Lq1_perm_done:
	v_mov_b32_e32 v0, v200
	s_cmpk_gt_i32 s30, 0xff
	v_ashrrev_i32_e32 v159, 8, v0
	s_cbranch_scc0 .LBB0_612
	s_cmpk_gt_u32 s30, 0x1ff
	s_cbranch_scc0 .LBB0_600
	s_cmpk_gt_u32 s30, 0x2ff
	s_cbranch_scc0 .LBB0_521
	s_lshl_b32 s31, s30, 1
	s_cmpk_gt_u32 s30, 0x3ff
	s_cbranch_scc0 .LBB0_509
	s_add_i32 s0, s31, 0xfffff800
	v_add_u32_e32 v0, s0, v159
	s_movk_i32 s0, 0x100
	v_lshlrev_b32_e32 v5, 5, v0
	v_cmp_gt_i32_e32 vcc, s0, v0
	v_mov_b32_e32 v0, 0x7ffffc00
	v_mov_b32_e32 v2, 0xffffff00
	v_mov_b32_e32 v4, v200
	v_cndmask_b32_e32 v0, v0, v2, vcc
	v_mov_b32_e32 v2, 0x400
	v_mov_b32_e32 v3, 0x100
	v_cndmask_b32_e32 v131, v2, v3, vcc
	v_lshrrev_b32_e32 v2, 1, v4
	v_and_b32_e32 v0, v0, v5
	v_and_b32_e32 v7, 24, v2
	v_mov_b64_e32 v[2:3], s[22:23]
	v_sub_u32_e32 v181, v5, v0
	v_mad_i64_i32 v[2:3], s[0:1], v0, s72, v[2:3]
	v_lshlrev_b32_e32 v0, 4, v4
	v_bfe_u32 v6, v4, 6, 2
	v_and_b32_e32 v0, 0xf0, v0
	v_lshl_or_b32 v0, v6, 8, v0
	v_lshl_add_u64 v[2:3], v[2:3], 0, v[0:1]
	s_mov_b64 s[0:1], 0x73800
	v_lshl_add_u64 v[32:33], v[2:3], 0, s[0:1]
	v_or_b32_e32 v2, v7, v5
	v_ashrrev_i32_e32 v3, 31, v2
	v_readlane_b32 s0, v254, 31
	v_lshlrev_b64 v[2:3], 10, v[2:3]
	v_readlane_b32 s1, v254, 32
	v_or_b32_e32 v167, v7, v181
	v_add_u32_e32 v179, -1, v131
	v_lshl_add_u64 v[2:3], s[0:1], 0, v[2:3]
	v_lshl_add_u64 v[30:31], v[2:3], 0, v[0:1]
	v_mov_b32_e32 v0, 63
	v_cmp_gt_u32_sdwa s[0:1], v4, v0 src0_sel:BYTE_0 src1_sel:DWORD
	s_and_saveexec_b64 s[2:3], s[0:1]
	s_xor_b64 s[88:89], exec, s[2:3]
	s_cbranch_execz .LBB0_506
	v_cmp_le_i32_e64 s[4:5], v167, v131
	v_cmp_lt_i32_e32 vcc, 1, v6
	s_mov_b64 s[74:75], 0
	s_mov_b64 s[0:1], 0
	s_and_saveexec_b64 s[2:3], vcc
	s_xor_b64 s[80:81], exec, s[2:3]
	s_cbranch_execz .LBB0_499
	v_cmp_eq_u32_e32 vcc, 2, v6
	s_mov_b64 s[0:1], -1
	s_and_saveexec_b64 s[82:83], vcc
	s_cbranch_execz .LBB0_498
	v_max_i32_e32 v0, 4, v167
	v_add_u32_e32 v2, -4, v0
	v_min_u32_e32 v2, v2, v179
	v_mad_u64_u32 v[2:3], s[0:1], v2, s72, v[32:33]
	v_add_u32_e32 v250, -4, v167
	v_max_i32_e32 v250, 0, v250
	v_min_u32_e32 v250, v250, v179
	v_mad_u64_u32 v[250:251], s[98:99], v250, s72, v[32:33]
	global_load_dwordx4 v[226:229], v[250:251], off
	v_add_u32_e32 v250, -3, v167
	v_max_i32_e32 v250, 0, v250
	v_min_u32_e32 v250, v250, v179
	v_mad_u64_u32 v[250:251], s[98:99], v250, s72, v[32:33]
	global_load_dwordx4 v[230:233], v[250:251], off
	v_add_u32_e32 v250, -2, v167
	v_max_i32_e32 v250, 0, v250
	v_min_u32_e32 v250, v250, v179
	v_mad_u64_u32 v[250:251], s[98:99], v250, s72, v[32:33]
	global_load_dwordx4 v[234:237], v[250:251], off
	v_add_u32_e32 v250, -1, v167
	v_max_i32_e32 v250, 0, v250
	v_min_u32_e32 v250, v250, v179
	v_mad_u64_u32 v[250:251], s[98:99], v250, s72, v[32:33]
	global_load_dwordx4 v[238:241], v[250:251], off
	v_add_u32_e32 v250, 0, v167
	v_max_i32_e32 v250, 0, v250
	v_min_u32_e32 v250, v250, v179
	v_mad_u64_u32 v[250:251], s[98:99], v250, s72, v[32:33]
	global_load_dwordx4 v[242:245], v[250:251], off
	v_add_u32_e32 v250, 1, v167
	v_max_i32_e32 v250, 0, v250
	v_min_u32_e32 v250, v250, v179
	v_mad_u64_u32 v[250:251], s[98:99], v250, s72, v[32:33]
	global_load_dwordx4 v[246:249], v[250:251], off
	v_cmp_lt_i32_e32 vcc, 3, v167
	s_and_b64 vcc, vcc, s[4:5]
	v_or_b32_e32 v35, 1, v167
	v_or_b32_e32 v34, 2, v167
	v_or_b32_e32 v23, 3, v167
	v_or_b32_e32 v97, 4, v167
	v_or_b32_e32 v22, 5, v167
	v_or_b32_e32 v14, 6, v167
	v_or_b32_e32 v83, 7, v167
	v_add_u32_e32 v110, 8, v167
	v_add_u32_e32 v116, 9, v167
	v_add_u32_e32 v105, 10, v167
	s_waitcnt vmcnt(5)
	v_cndmask_b32_e32 v8, 0, v226, vcc
	v_add_u32_e32 v2, -3, v167
	v_cmp_lt_i32_e64 s[0:1], v2, v131
	v_max_i32_e32 v2, 0, v2
	v_cndmask_b32_e32 v9, 0, v227, vcc
	v_cndmask_b32_e32 v7, 0, v228, vcc
	v_cndmask_b32_e32 v6, 0, v229, vcc
	v_add_u32_e32 v250, 2, v167
	v_max_i32_e32 v250, 0, v250
	v_min_u32_e32 v250, v250, v179
	v_mad_u64_u32 v[250:251], s[98:99], v250, s72, v[32:33]
	global_load_dwordx4 v[226:229], v[250:251], off
	v_cmp_lt_i32_e32 vcc, 2, v167
	v_min_u32_e32 v2, v2, v179
	s_and_b64 vcc, vcc, s[0:1]
	v_mad_u64_u32 v[2:3], s[0:1], v2, s72, v[32:33]
	v_lshlrev_b32_e32 v26, 16, v6
	v_and_b32_e32 v27, 0xffff0000, v6
	v_min_i32_e32 v6, v97, v131
	v_sub_u32_e32 v0, v6, v0
	v_add_u32_e32 v0, 4, v0
	v_cvt_f32_i32_e32 v0, v0
	s_waitcnt vmcnt(5)
	v_cndmask_b32_e32 v11, 0, v230, vcc
	v_max_i32_e32 v2, 2, v167
	v_add_u32_e32 v2, -2, v2
	v_min_u32_e32 v2, v2, v179
	v_cndmask_b32_e32 v12, 0, v231, vcc
	v_mad_u64_u32 v[2:3], s[0:1], v2, s72, v[32:33]
	v_cndmask_b32_e32 v13, 0, v232, vcc
	v_cndmask_b32_e32 v15, 0, v233, vcc
	v_add_u32_e32 v250, 3, v167
	v_max_i32_e32 v250, 0, v250
	v_min_u32_e32 v250, v250, v179
	v_mad_u64_u32 v[250:251], s[98:99], v250, s72, v[32:33]
	global_load_dwordx4 v[230:233], v[250:251], off
	v_cmp_lt_i32_e32 vcc, 1, v167
	s_and_b64 vcc, vcc, s[4:5]
	v_lshlrev_b32_e32 v28, 16, v15
	v_and_b32_e32 v29, 0xffff0000, v15
	v_lshlrev_b32_e32 v10, 16, v11
	v_and_b32_e32 v11, 0xffff0000, v11
	v_lshlrev_b32_e32 v16, 16, v12
	v_and_b32_e32 v17, 0xffff0000, v12
	v_lshlrev_b32_e32 v12, 16, v13
	v_and_b32_e32 v13, 0xffff0000, v13
	s_waitcnt vmcnt(5)
	v_cndmask_b32_e32 v21, 0, v234, vcc
	v_max_i32_e32 v2, 1, v167
	v_add_u32_e32 v2, -1, v2
	v_min_u32_e32 v2, v2, v179
	v_cndmask_b32_e32 v20, 0, v235, vcc
	v_mad_u64_u32 v[2:3], s[0:1], v2, s72, v[32:33]
	v_cndmask_b32_e32 v19, 0, v236, vcc
	v_cndmask_b32_e32 v18, 0, v237, vcc
	v_add_u32_e32 v250, 4, v167
	v_max_i32_e32 v250, 0, v250
	v_min_u32_e32 v250, v250, v179
	v_mad_u64_u32 v[250:251], s[98:99], v250, s72, v[32:33]
	global_load_dwordx4 v[234:237], v[250:251], off
	v_cmp_lt_i32_e32 vcc, 0, v167
	s_and_b64 vcc, vcc, s[4:5]
	v_cmp_lt_i32_e64 s[0:1], v167, v131
	v_lshlrev_b32_e32 v42, 16, v21
	v_and_b32_e32 v43, 0xffff0000, v21
	v_lshlrev_b32_e32 v24, 16, v20
	v_and_b32_e32 v25, 0xffff0000, v20
	v_lshlrev_b32_e32 v20, 16, v19
	v_and_b32_e32 v21, 0xffff0000, v19
	v_lshlrev_b32_e32 v46, 16, v18
	v_and_b32_e32 v47, 0xffff0000, v18
	s_waitcnt vmcnt(5)
	v_cndmask_b32_e32 v39, 0, v238, vcc
	v_max_i32_e32 v2, 0, v167
	v_cndmask_b32_e32 v38, 0, v239, vcc
	v_cndmask_b32_e32 v37, 0, v240, vcc
	v_cndmask_b32_e32 v36, 0, v241, vcc
	v_add_u32_e32 v250, 5, v167
	v_max_i32_e32 v250, 0, v250
	v_min_u32_e32 v250, v250, v179
	v_mad_u64_u32 v[250:251], s[98:99], v250, s72, v[32:33]
	global_load_dwordx4 v[238:241], v[250:251], off
	v_cmp_lt_i32_e32 vcc, -1, v181
	v_min_u32_e32 v2, v2, v179
	s_and_b64 vcc, vcc, s[0:1]
	v_mad_u64_u32 v[2:3], s[0:1], v2, s72, v[32:33]
	v_cmp_lt_i32_e64 s[0:1], v35, v131
	v_lshlrev_b32_e32 v48, 16, v36
	v_and_b32_e32 v49, 0xffff0000, v36
	v_lshlrev_b32_e32 v58, 16, v37
	v_and_b32_e32 v59, 0xffff0000, v37
	v_lshlrev_b32_e32 v18, 16, v39
	v_and_b32_e32 v19, 0xffff0000, v39
	v_lshlrev_b32_e32 v44, 16, v38
	v_and_b32_e32 v45, 0xffff0000, v38
	s_waitcnt vmcnt(5)
	v_cndmask_b32_e32 v51, 0, v242, vcc
	v_max_i32_e32 v2, 0, v35
	v_cndmask_b32_e32 v50, 0, v243, vcc
	v_cndmask_b32_e32 v41, 0, v244, vcc
	v_cndmask_b32_e32 v40, 0, v245, vcc
	v_add_u32_e32 v250, 6, v167
	v_max_i32_e32 v250, 0, v250
	v_min_u32_e32 v250, v250, v179
	v_mad_u64_u32 v[250:251], s[98:99], v250, s72, v[32:33]
	global_load_dwordx4 v[242:245], v[250:251], off
	v_cmp_lt_i32_e32 vcc, -2, v167
	v_min_u32_e32 v2, v2, v179
	s_and_b64 vcc, vcc, s[0:1]
	v_mad_u64_u32 v[2:3], s[0:1], v2, s72, v[32:33]
	v_cmp_lt_i32_e64 s[0:1], v34, v131
	v_lshlrev_b32_e32 v84, 16, v51
	v_and_b32_e32 v85, 0xffff0000, v51
	v_lshlrev_b32_e32 v70, 16, v50
	v_and_b32_e32 v71, 0xffff0000, v50
	v_lshlrev_b32_e32 v60, 16, v41
	v_and_b32_e32 v61, 0xffff0000, v41
	v_lshlrev_b32_e32 v50, 16, v40
	v_and_b32_e32 v51, 0xffff0000, v40
	s_waitcnt vmcnt(5)
	v_cndmask_b32_e32 v55, 0, v246, vcc
	v_max_i32_e32 v2, 0, v34
	v_cndmask_b32_e32 v54, 0, v247, vcc
	v_cndmask_b32_e32 v52, 0, v248, vcc
	v_cndmask_b32_e32 v53, 0, v249, vcc
	v_add_u32_e32 v250, 7, v167
	v_max_i32_e32 v250, 0, v250
	v_min_u32_e32 v250, v250, v179
	v_mad_u64_u32 v[250:251], s[98:99], v250, s72, v[32:33]
	global_load_dwordx4 v[246:249], v[250:251], off
	v_cmp_lt_i32_e32 vcc, -3, v167
	v_min_u32_e32 v2, v2, v179
	s_and_b64 vcc, vcc, s[0:1]
	v_mad_u64_u32 v[2:3], s[0:1], v2, s72, v[32:33]
	v_cmp_lt_i32_e64 s[0:1], v23, v131
	v_lshlrev_b32_e32 v86, 16, v55
	v_and_b32_e32 v87, 0xffff0000, v55
	v_lshlrev_b32_e32 v72, 16, v54
	v_and_b32_e32 v73, 0xffff0000, v54
	v_lshlrev_b32_e32 v62, 16, v52
	v_and_b32_e32 v63, 0xffff0000, v52
	v_lshlrev_b32_e32 v52, 16, v53
	v_and_b32_e32 v53, 0xffff0000, v53
	s_waitcnt vmcnt(5)
	v_cndmask_b32_e32 v65, 0, v226, vcc
	v_max_i32_e32 v2, 0, v23
	v_cndmask_b32_e32 v64, 0, v227, vcc
	v_cndmask_b32_e32 v57, 0, v228, vcc
	v_cndmask_b32_e32 v56, 0, v229, vcc
	v_add_u32_e32 v250, 8, v167
	v_max_i32_e32 v250, 0, v250
	v_min_u32_e32 v250, v250, v179
	v_mad_u64_u32 v[250:251], s[98:99], v250, s72, v[32:33]
	global_load_dwordx4 v[226:229], v[250:251], off
	v_cmp_lt_i32_e32 vcc, -4, v167
	v_min_u32_e32 v2, v2, v179
	s_and_b64 vcc, vcc, s[0:1]
	v_mad_u64_u32 v[2:3], s[0:1], v2, s72, v[32:33]
	v_cmp_lt_i32_e64 s[0:1], v97, v131
	v_lshlrev_b32_e32 v88, 16, v65
	v_and_b32_e32 v89, 0xffff0000, v65
	v_lshlrev_b32_e32 v74, 16, v64
	v_and_b32_e32 v75, 0xffff0000, v64
	v_lshlrev_b32_e32 v64, 16, v57
	v_and_b32_e32 v65, 0xffff0000, v57
	v_lshlrev_b32_e32 v54, 16, v56
	v_and_b32_e32 v55, 0xffff0000, v56
	s_waitcnt vmcnt(5)
	v_cndmask_b32_e32 v69, 0, v230, vcc
	v_max_i32_e32 v2, 0, v97
	v_cndmask_b32_e32 v68, 0, v231, vcc
	v_cndmask_b32_e32 v67, 0, v232, vcc
	v_cndmask_b32_e32 v66, 0, v233, vcc
	v_add_u32_e32 v250, 9, v167
	v_max_i32_e32 v250, 0, v250
	v_min_u32_e32 v250, v250, v179
	v_mad_u64_u32 v[250:251], s[98:99], v250, s72, v[32:33]
	global_load_dwordx4 v[230:233], v[250:251], off
	v_cmp_lt_i32_e32 vcc, -5, v167
	v_min_u32_e32 v2, v2, v179
	s_and_b64 vcc, vcc, s[0:1]
	v_mad_u64_u32 v[2:3], s[0:1], v2, s72, v[32:33]
	v_cmp_lt_i32_e64 s[0:1], v22, v131
	v_lshlrev_b32_e32 v98, 16, v69
	v_and_b32_e32 v99, 0xffff0000, v69
	v_lshlrev_b32_e32 v80, 16, v68
	v_and_b32_e32 v81, 0xffff0000, v68
	v_lshlrev_b32_e32 v68, 16, v67
	v_and_b32_e32 v69, 0xffff0000, v67
	v_lshlrev_b32_e32 v56, 16, v66
	v_and_b32_e32 v57, 0xffff0000, v66
	s_waitcnt vmcnt(5)
	v_cndmask_b32_e32 v94, 0, v234, vcc
	v_max_i32_e32 v2, 0, v22
	v_cndmask_b32_e32 v76, 0, v235, vcc
	v_cndmask_b32_e32 v77, 0, v236, vcc
	v_cndmask_b32_e32 v82, 0, v237, vcc
	v_add_u32_e32 v250, 10, v167
	v_max_i32_e32 v250, 0, v250
	v_min_u32_e32 v250, v250, v179
	v_mad_u64_u32 v[250:251], s[98:99], v250, s72, v[32:33]
	global_load_dwordx4 v[234:237], v[250:251], off
	v_cmp_lt_i32_e32 vcc, -6, v167
	v_min_u32_e32 v2, v2, v179
	s_and_b64 vcc, vcc, s[0:1]
	v_mad_u64_u32 v[2:3], s[0:1], v2, s72, v[32:33]
	v_cmp_lt_i32_e64 s[0:1], v14, v131
	v_lshlrev_b32_e32 v66, 16, v82
	v_and_b32_e32 v67, 0xffff0000, v82
	v_lshlrev_b32_e32 v106, 16, v94
	v_and_b32_e32 v107, 0xffff0000, v94
	v_lshlrev_b32_e32 v94, 16, v76
	v_and_b32_e32 v95, 0xffff0000, v76
	v_lshlrev_b32_e32 v76, 16, v77
	v_and_b32_e32 v77, 0xffff0000, v77
	s_waitcnt vmcnt(5)
	v_cndmask_b32_e32 v93, 0, v238, vcc
	v_max_i32_e32 v2, 0, v14
	v_cndmask_b32_e32 v92, 0, v239, vcc
	v_cndmask_b32_e32 v78, 0, v240, vcc
	v_cndmask_b32_e32 v79, 0, v241, vcc
	v_cmp_lt_i32_e32 vcc, -7, v167
	v_min_u32_e32 v2, v2, v179
	s_and_b64 vcc, vcc, s[0:1]
	v_mad_u64_u32 v[2:3], s[0:1], v2, s72, v[32:33]
	v_cmp_lt_i32_e64 s[0:1], v83, v131
	v_lshlrev_b32_e32 v112, 16, v93
	v_and_b32_e32 v113, 0xffff0000, v93
	v_lshlrev_b32_e32 v102, 16, v92
	v_and_b32_e32 v103, 0xffff0000, v92
	v_lshlrev_b32_e32 v92, 16, v78
	v_and_b32_e32 v93, 0xffff0000, v78
	v_lshlrev_b32_e32 v78, 16, v79
	v_and_b32_e32 v79, 0xffff0000, v79
	s_waitcnt vmcnt(4)
	v_cndmask_b32_e32 v101, 0, v242, vcc
	v_max_i32_e32 v2, 0, v83
	v_cndmask_b32_e32 v100, 0, v243, vcc
	v_cndmask_b32_e32 v90, 0, v244, vcc
	v_cndmask_b32_e32 v91, 0, v245, vcc
	v_cmp_lt_i32_e32 vcc, -8, v167
	v_min_u32_e32 v2, v2, v179
	s_and_b64 vcc, vcc, s[0:1]
	v_mad_u64_u32 v[2:3], s[0:1], v2, s72, v[32:33]
	v_cmp_lt_i32_e64 s[0:1], v110, v131
	v_lshlrev_b32_e32 v118, 16, v101
	v_and_b32_e32 v119, 0xffff0000, v101
	v_lshlrev_b32_e32 v108, 16, v100
	v_and_b32_e32 v109, 0xffff0000, v100
	v_lshlrev_b32_e32 v100, 16, v90
	v_and_b32_e32 v101, 0xffff0000, v90
	v_lshlrev_b32_e32 v90, 16, v91
	v_and_b32_e32 v91, 0xffff0000, v91
	s_waitcnt vmcnt(3)
	v_cndmask_b32_e32 v127, 0, v246, vcc
	v_max_i32_e32 v2, 0, v110
	v_cndmask_b32_e32 v126, 0, v247, vcc
	v_cndmask_b32_e32 v125, 0, v248, vcc
	v_cndmask_b32_e32 v124, 0, v249, vcc
	v_cmp_lt_i32_e32 vcc, -9, v167
	v_min_u32_e32 v2, v2, v179
	s_and_b64 vcc, vcc, s[0:1]
	v_mad_u64_u32 v[2:3], s[0:1], v2, s72, v[32:33]
	v_cmp_lt_i32_e64 s[0:1], v116, v131
	v_lshlrev_b32_e32 v38, 16, v126
	v_and_b32_e32 v39, 0xffff0000, v126
	v_lshlrev_b32_e32 v40, 16, v125
	v_and_b32_e32 v41, 0xffff0000, v125
	s_waitcnt vmcnt(2)
	v_cndmask_b32_e32 v123, 0, v226, vcc
	v_max_i32_e32 v2, 0, v116
	v_cndmask_b32_e32 v122, 0, v227, vcc
	v_cndmask_b32_e32 v114, 0, v228, vcc
	v_cndmask_b32_e32 v115, 0, v229, vcc
	v_cmp_lt_i32_e32 vcc, -10, v167
	v_min_u32_e32 v2, v2, v179
	s_and_b64 vcc, vcc, s[0:1]
	v_mad_u64_u32 v[2:3], s[0:1], v2, s72, v[32:33]
	v_cmp_lt_i32_e64 s[0:1], v105, v131
	v_lshlrev_b32_e32 v140, 16, v123
	v_and_b32_e32 v141, 0xffff0000, v123
	v_lshlrev_b32_e32 v132, 16, v122
	v_and_b32_e32 v133, 0xffff0000, v122
	v_lshlrev_b32_e32 v122, 16, v114
	v_and_b32_e32 v123, 0xffff0000, v114
	v_lshlrev_b32_e32 v114, 16, v115
	v_and_b32_e32 v115, 0xffff0000, v115
	s_waitcnt vmcnt(1)
	v_cndmask_b32_e32 v121, 0, v230, vcc
	v_max_i32_e32 v2, 0, v105
	v_cndmask_b32_e32 v120, 0, v231, vcc
	v_cndmask_b32_e32 v117, 0, v232, vcc
	v_cndmask_b32_e32 v111, 0, v233, vcc
	v_cmp_lt_i32_e32 vcc, -11, v167
	v_min_u32_e32 v2, v2, v179
	s_and_b64 vcc, vcc, s[0:1]
	v_mad_u64_u32 v[2:3], s[0:1], v2, s72, v[32:33]
	v_div_scale_f32 v6, s[0:1], v0, v0, 1.0
	v_lshlrev_b32_e32 v142, 16, v121
	v_and_b32_e32 v143, 0xffff0000, v121
	v_lshlrev_b32_e32 v144, 16, v120
	v_and_b32_e32 v145, 0xffff0000, v120
	v_lshlrev_b32_e32 v128, 16, v117
	v_and_b32_e32 v129, 0xffff0000, v117
	v_lshlrev_b32_e32 v120, 16, v111
	v_and_b32_e32 v121, 0xffff0000, v111
	s_waitcnt vmcnt(0)
	v_cndmask_b32_e32 v135, 0, v236, vcc
	v_cndmask_b32_e32 v134, 0, v237, vcc
	v_lshlrev_b32_e32 v4, 16, v7
	v_and_b32_e32 v5, 0xffff0000, v7
	v_rcp_f32_e32 v7, v6
	v_cndmask_b32_e32 v137, 0, v234, vcc
	v_cndmask_b32_e32 v136, 0, v235, vcc
	v_lshlrev_b32_e32 v2, 16, v8
	v_fma_f32 v15, -v6, v7, 1.0
	v_fmac_f32_e32 v7, v15, v7
	v_div_scale_f32 v15, vcc, 1.0, v0, 1.0
	v_mul_f32_e32 v36, v15, v7
	v_fma_f32 v37, -v6, v36, v15
	v_fmac_f32_e32 v36, v37, v7
	v_fma_f32 v6, -v6, v36, v15
	v_div_fmas_f32 v6, v6, v7, v36
	v_div_fixup_f32 v0, v6, v0, 1.0
	v_max_i32_e32 v6, 4, v35
	v_min_i32_e32 v7, v22, v131
	v_sub_u32_e32 v6, v7, v6
	v_add_u32_e32 v6, 4, v6
	v_cvt_f32_i32_e32 v6, v6
	v_and_b32_e32 v3, 0xffff0000, v8
	v_lshlrev_b32_e32 v8, 16, v9
	v_and_b32_e32 v9, 0xffff0000, v9
	v_div_scale_f32 v7, s[0:1], v6, v6, 1.0
	v_rcp_f32_e32 v15, v7
	v_lshlrev_b32_e32 v146, 16, v137
	v_and_b32_e32 v147, 0xffff0000, v137
	v_and_b32_e32 v125, 0xffff0000, v134
	v_fma_f32 v35, -v7, v15, 1.0
	v_fmac_f32_e32 v15, v35, v15
	v_div_scale_f32 v35, vcc, 1.0, v6, 1.0
	v_mul_f32_e32 v36, v35, v15
	v_fma_f32 v37, -v7, v36, v35
	v_fmac_f32_e32 v36, v37, v15
	v_fma_f32 v7, -v7, v36, v35
	v_div_fmas_f32 v7, v7, v15, v36
	v_div_fixup_f32 v82, v7, v6, 1.0
	v_max_i32_e32 v6, 4, v34
	v_min_i32_e32 v7, v14, v131
	v_sub_u32_e32 v6, v7, v6
	v_add_u32_e32 v6, 4, v6
	v_cvt_f32_i32_e32 v6, v6
	v_and_b32_e32 v37, 0xffff0000, v124
	v_div_scale_f32 v7, s[0:1], v6, v6, 1.0
	v_rcp_f32_e32 v15, v7
	s_nop 0
	v_fma_f32 v34, -v7, v15, 1.0
	v_fmac_f32_e32 v15, v34, v15
	v_div_scale_f32 v34, vcc, 1.0, v6, 1.0
	v_mul_f32_e32 v35, v34, v15
	v_fma_f32 v36, -v7, v35, v34
	v_fmac_f32_e32 v35, v36, v15
	v_fma_f32 v7, -v7, v35, v34
	v_div_fmas_f32 v7, v7, v15, v35
	v_div_fixup_f32 v96, v7, v6, 1.0
	v_max_i32_e32 v6, 4, v23
	v_min_i32_e32 v7, v83, v131
	v_sub_u32_e32 v6, v7, v6
	v_add_u32_e32 v6, 4, v6
	v_cvt_f32_i32_e32 v6, v6
	v_lshlrev_b32_e32 v36, 16, v124
	v_lshlrev_b32_e32 v124, 16, v134
	v_div_scale_f32 v7, s[0:1], v6, v6, 1.0
	v_rcp_f32_e32 v15, v7
	s_nop 0
	v_fma_f32 v23, -v7, v15, 1.0
	v_fmac_f32_e32 v15, v23, v15
	v_div_scale_f32 v23, vcc, 1.0, v6, 1.0
	v_mul_f32_e32 v34, v23, v15
	v_fma_f32 v35, -v7, v34, v23
	v_fmac_f32_e32 v34, v35, v15
	v_fma_f32 v7, -v7, v34, v23
	v_div_fmas_f32 v7, v7, v15, v34
	v_div_fixup_f32 v104, v7, v6, 1.0
	v_max_i32_e32 v6, 4, v97
	v_min_i32_e32 v7, v110, v131
	v_sub_u32_e32 v6, v7, v6
	v_add_u32_e32 v6, 4, v6
	v_cvt_f32_i32_e32 v6, v6
	v_lshlrev_b32_e32 v34, 16, v127
	v_and_b32_e32 v35, 0xffff0000, v127
	v_div_scale_f32 v7, s[0:1], v6, v6, 1.0
	v_rcp_f32_e32 v15, v7
	s_nop 0
	v_fma_f32 v23, -v7, v15, 1.0
	v_fmac_f32_e32 v15, v23, v15
	v_div_scale_f32 v23, vcc, 1.0, v6, 1.0
	v_mul_f32_e32 v97, v23, v15
	v_fma_f32 v110, -v7, v97, v23
	v_fmac_f32_e32 v97, v110, v15
	v_fma_f32 v7, -v7, v97, v23
	v_div_fmas_f32 v7, v7, v15, v97
	v_div_fixup_f32 v110, v7, v6, 1.0
	v_max_i32_e32 v6, 4, v22
	v_min_i32_e32 v7, v116, v131
	v_sub_u32_e32 v6, v7, v6
	v_add_u32_e32 v6, 4, v6
	v_cvt_f32_i32_e32 v6, v6
	v_div_scale_f32 v7, s[0:1], v6, v6, 1.0
	v_rcp_f32_e32 v15, v7
	s_nop 0
	v_fma_f32 v22, -v7, v15, 1.0
	v_fmac_f32_e32 v15, v22, v15
	v_div_scale_f32 v22, vcc, 1.0, v6, 1.0
	v_mul_f32_e32 v23, v22, v15
	v_fma_f32 v97, -v7, v23, v22
	v_fmac_f32_e32 v23, v97, v15
	v_fma_f32 v7, -v7, v23, v22
	v_div_fmas_f32 v7, v7, v15, v23
	v_div_fixup_f32 v116, v7, v6, 1.0
	v_max_i32_e32 v6, 4, v14
	v_min_i32_e32 v7, v105, v131
	v_sub_u32_e32 v6, v7, v6
	v_add_u32_e32 v6, 4, v6
	v_cvt_f32_i32_e32 v6, v6
	v_div_scale_f32 v7, s[0:1], v6, v6, 1.0
	v_rcp_f32_e32 v14, v7
	s_xor_b64 s[0:1], exec, -1
	v_fma_f32 v15, -v7, v14, 1.0
	v_fmac_f32_e32 v14, v15, v14
	v_div_scale_f32 v15, vcc, 1.0, v6, 1.0
	v_mul_f32_e32 v22, v15, v14
	v_fma_f32 v23, -v7, v22, v15
	v_fmac_f32_e32 v22, v23, v14
	v_fma_f32 v7, -v7, v22, v15
	v_div_fmas_f32 v7, v7, v14, v22
	v_div_fixup_f32 v126, v7, v6, 1.0
	v_pk_add_f32 v[6:7], v[2:3], 0 op_sel_hi:[1,0]
	v_pk_add_f32 v[2:3], v[106:107], v[2:3] neg_lo:[0,1] neg_hi:[0,1]
	v_pk_add_f32 v[6:7], v[6:7], v[10:11]
	v_pk_add_f32 v[10:11], v[112:113], v[10:11] neg_lo:[0,1] neg_hi:[0,1]
	v_pk_add_f32 v[6:7], v[6:7], v[42:43]
	s_nop 0
	v_pk_add_f32 v[6:7], v[6:7], v[18:19]
	s_nop 0
	v_pk_add_f32 v[6:7], v[6:7], v[84:85]
	s_nop 0
	v_pk_add_f32 v[6:7], v[6:7], v[86:87]
	s_nop 0
	v_pk_add_f32 v[6:7], v[6:7], v[88:89]
	s_nop 0
	v_pk_add_f32 v[14:15], v[6:7], v[98:99]
	s_nop 0
	v_pk_add_f32 v[2:3], v[14:15], v[2:3]
	v_pk_fma_f32 v[6:7], v[0:1], v[14:15], v[84:85] op_sel_hi:[0,1,1] neg_lo:[0,0,1] neg_hi:[0,0,1]
	v_pk_fma_f32 v[14:15], v[82:83], v[2:3], v[86:87] op_sel_hi:[0,1,1] neg_lo:[0,0,1] neg_hi:[0,0,1]
	v_pk_add_f32 v[2:3], v[2:3], v[10:11]
	v_cvt_pk_bf16_f32 v6, v6, v7
	v_pk_fma_f32 v[10:11], v[96:97], v[2:3], v[88:89] op_sel_hi:[0,1,1] neg_lo:[0,0,1] neg_hi:[0,0,1]
	v_cvt_pk_bf16_f32 v22, v10, v11
	v_pk_add_f32 v[10:11], v[118:119], v[42:43] neg_lo:[0,1] neg_hi:[0,1]
	v_pk_add_f32 v[42:43], v[142:143], v[86:87] neg_lo:[0,1] neg_hi:[0,1]
	v_pk_add_f32 v[86:87], v[8:9], 0 op_sel_hi:[1,0]
	v_pk_add_f32 v[2:3], v[2:3], v[10:11]
	v_pk_add_f32 v[86:87], v[86:87], v[16:17]
	v_pk_add_f32 v[8:9], v[94:95], v[8:9] neg_lo:[0,1] neg_hi:[0,1]
	v_pk_add_f32 v[86:87], v[86:87], v[24:25]
	v_pk_fma_f32 v[10:11], v[104:105], v[2:3], v[98:99] op_sel_hi:[0,1,1] neg_lo:[0,0,1] neg_hi:[0,0,1]
	v_pk_add_f32 v[86:87], v[86:87], v[44:45]
	v_pk_add_f32 v[16:17], v[102:103], v[16:17] neg_lo:[0,1] neg_hi:[0,1]
	v_pk_add_f32 v[86:87], v[86:87], v[70:71]
	v_cvt_pk_bf16_f32 v138, v10, v11
	v_pk_add_f32 v[86:87], v[86:87], v[72:73]
	v_pk_add_f32 v[10:11], v[34:35], v[18:19] neg_lo:[0,1] neg_hi:[0,1]
	v_pk_add_f32 v[86:87], v[86:87], v[74:75]
	v_pk_add_f32 v[18:19], v[140:141], v[84:85] neg_lo:[0,1] neg_hi:[0,1]
	v_pk_add_f32 v[86:87], v[86:87], v[80:81]
	v_pk_add_f32 v[84:85], v[146:147], v[88:89] neg_lo:[0,1] neg_hi:[0,1]
	v_pk_add_f32 v[8:9], v[86:87], v[8:9]
	v_pk_fma_f32 v[88:89], v[0:1], v[86:87], v[70:71] op_sel_hi:[0,1,1] neg_lo:[0,0,1] neg_hi:[0,0,1]
	v_pk_fma_f32 v[86:87], v[82:83], v[8:9], v[72:73] op_sel_hi:[0,1,1] neg_lo:[0,0,1] neg_hi:[0,0,1]
	v_pk_add_f32 v[8:9], v[8:9], v[16:17]
	v_pk_add_f32 v[10:11], v[2:3], v[10:11]
	v_pk_fma_f32 v[16:17], v[96:97], v[8:9], v[74:75] op_sel_hi:[0,1,1] neg_lo:[0,0,1] neg_hi:[0,0,1]
	v_cvt_pk_bf16_f32 v23, v16, v17
	v_pk_add_f32 v[16:17], v[108:109], v[24:25] neg_lo:[0,1] neg_hi:[0,1]
	v_pk_fma_f32 v[2:3], v[110:111], v[10:11], v[106:107] op_sel_hi:[0,1,1] neg_lo:[0,0,1] neg_hi:[0,0,1]
	v_pk_add_f32 v[8:9], v[8:9], v[16:17]
	v_cvt_pk_bf16_f32 v2, v2, v3
	v_pk_fma_f32 v[16:17], v[104:105], v[8:9], v[80:81] op_sel_hi:[0,1,1] neg_lo:[0,0,1] neg_hi:[0,0,1]
	v_cvt_pk_bf16_f32 v139, v16, v17
	v_pk_add_f32 v[16:17], v[38:39], v[44:45] neg_lo:[0,1] neg_hi:[0,1]
	v_pk_add_f32 v[18:19], v[10:11], v[18:19]
	v_pk_add_f32 v[8:9], v[8:9], v[16:17]
	v_pk_fma_f32 v[10:11], v[116:117], v[18:19], v[112:113] op_sel_hi:[0,1,1] neg_lo:[0,0,1] neg_hi:[0,0,1]
	v_pk_fma_f32 v[16:17], v[110:111], v[8:9], v[94:95] op_sel_hi:[0,1,1] neg_lo:[0,0,1] neg_hi:[0,0,1]
	v_cvt_pk_bf16_f32 v3, v16, v17
	v_pk_add_f32 v[16:17], v[132:133], v[70:71] neg_lo:[0,1] neg_hi:[0,1]
	v_cvt_pk_bf16_f32 v10, v10, v11
	v_pk_add_f32 v[8:9], v[8:9], v[16:17]
	v_pk_add_f32 v[42:43], v[18:19], v[42:43]
	v_pk_fma_f32 v[16:17], v[116:117], v[8:9], v[102:103] op_sel_hi:[0,1,1] neg_lo:[0,0,1] neg_hi:[0,0,1]
	v_cvt_pk_bf16_f32 v11, v16, v17
	v_pk_add_f32 v[16:17], v[144:145], v[72:73] neg_lo:[0,1] neg_hi:[0,1]
	v_pk_fma_f32 v[18:19], v[126:127], v[42:43], v[118:119] op_sel_hi:[0,1,1] neg_lo:[0,0,1] neg_hi:[0,0,1]
	v_pk_add_f32 v[8:9], v[8:9], v[16:17]
	v_pk_add_f32 v[42:43], v[42:43], v[84:85]
	v_lshlrev_b32_e32 v84, 16, v136
	v_and_b32_e32 v85, 0xffff0000, v136
	v_pk_fma_f32 v[16:17], v[126:127], v[8:9], v[108:109] op_sel_hi:[0,1,1] neg_lo:[0,0,1] neg_hi:[0,0,1]
	v_cvt_pk_bf16_f32 v18, v18, v19
	v_cvt_pk_bf16_f32 v19, v16, v17
	v_pk_add_f32 v[16:17], v[84:85], v[74:75] neg_lo:[0,1] neg_hi:[0,1]
	v_lshlrev_b32_e32 v70, 16, v135
	v_pk_add_f32 v[44:45], v[8:9], v[16:17]
	v_pk_add_f32 v[8:9], v[4:5], 0 op_sel_hi:[1,0]
	v_pk_add_f32 v[4:5], v[76:77], v[4:5] neg_lo:[0,1] neg_hi:[0,1]
	v_pk_add_f32 v[8:9], v[8:9], v[12:13]
	v_pk_add_f32 v[12:13], v[92:93], v[12:13] neg_lo:[0,1] neg_hi:[0,1]
	v_pk_add_f32 v[8:9], v[8:9], v[20:21]
	v_and_b32_e32 v71, 0xffff0000, v135
	v_pk_add_f32 v[8:9], v[8:9], v[58:59]
	v_cvt_pk_bf16_f32 v7, v88, v89
	v_pk_add_f32 v[8:9], v[8:9], v[60:61]
	v_cvt_pk_bf16_f32 v14, v14, v15
	v_pk_add_f32 v[8:9], v[8:9], v[62:63]
	v_cvt_pk_bf16_f32 v15, v86, v87
	v_pk_add_f32 v[8:9], v[8:9], v[64:65]
	s_nop 0
	v_pk_add_f32 v[16:17], v[8:9], v[68:69]
	s_nop 0
	v_pk_add_f32 v[4:5], v[16:17], v[4:5]
	v_pk_fma_f32 v[8:9], v[0:1], v[16:17], v[60:61] op_sel_hi:[0,1,1] neg_lo:[0,0,1] neg_hi:[0,0,1]
	v_pk_fma_f32 v[16:17], v[82:83], v[4:5], v[62:63] op_sel_hi:[0,1,1] neg_lo:[0,0,1] neg_hi:[0,0,1]
	v_pk_add_f32 v[4:5], v[4:5], v[12:13]
	v_cvt_pk_bf16_f32 v8, v8, v9
	v_pk_fma_f32 v[12:13], v[96:97], v[4:5], v[64:65] op_sel_hi:[0,1,1] neg_lo:[0,0,1] neg_hi:[0,0,1]
	v_cvt_pk_bf16_f32 v24, v12, v13
	v_pk_add_f32 v[12:13], v[100:101], v[20:21] neg_lo:[0,1] neg_hi:[0,1]
	v_pk_add_f32 v[20:21], v[122:123], v[60:61] neg_lo:[0,1] neg_hi:[0,1]
	v_pk_add_f32 v[4:5], v[4:5], v[12:13]
	v_pk_add_f32 v[60:61], v[70:71], v[64:65] neg_lo:[0,1] neg_hi:[0,1]
	v_pk_fma_f32 v[12:13], v[104:105], v[4:5], v[68:69] op_sel_hi:[0,1,1] neg_lo:[0,0,1] neg_hi:[0,0,1]
	v_cvt_pk_bf16_f32 v140, v12, v13
	v_pk_add_f32 v[12:13], v[40:41], v[58:59] neg_lo:[0,1] neg_hi:[0,1]
	v_pk_add_f32 v[58:59], v[128:129], v[62:63] neg_lo:[0,1] neg_hi:[0,1]
	v_pk_add_f32 v[12:13], v[4:5], v[12:13]
	v_cvt_pk_bf16_f32 v16, v16, v17
	v_pk_add_f32 v[20:21], v[12:13], v[20:21]
	v_pk_fma_f32 v[4:5], v[110:111], v[12:13], v[76:77] op_sel_hi:[0,1,1] neg_lo:[0,0,1] neg_hi:[0,0,1]
	v_pk_add_f32 v[58:59], v[20:21], v[58:59]
	v_pk_fma_f32 v[12:13], v[116:117], v[20:21], v[92:93] op_sel_hi:[0,1,1] neg_lo:[0,0,1] neg_hi:[0,0,1]
	v_pk_fma_f32 v[20:21], v[126:127], v[58:59], v[100:101] op_sel_hi:[0,1,1] neg_lo:[0,0,1] neg_hi:[0,0,1]
	v_pk_add_f32 v[76:77], v[58:59], v[60:61]
	v_pk_add_f32 v[58:59], v[26:27], 0 op_sel_hi:[1,0]
	v_pk_add_f32 v[26:27], v[66:67], v[26:27] neg_lo:[0,1] neg_hi:[0,1]
	v_pk_add_f32 v[58:59], v[58:59], v[28:29]
	v_pk_add_f32 v[28:29], v[78:79], v[28:29] neg_lo:[0,1] neg_hi:[0,1]
	v_pk_add_f32 v[58:59], v[58:59], v[46:47]
	v_cvt_pk_bf16_f32 v4, v4, v5
	v_pk_add_f32 v[58:59], v[58:59], v[48:49]
	v_cvt_pk_bf16_f32 v12, v12, v13
	v_pk_add_f32 v[58:59], v[58:59], v[50:51]
	v_cvt_pk_bf16_f32 v20, v20, v21
	v_pk_add_f32 v[58:59], v[58:59], v[52:53]
	s_nop 0
	v_pk_add_f32 v[58:59], v[58:59], v[54:55]
	s_nop 0
	v_pk_add_f32 v[58:59], v[58:59], v[56:57]
	s_nop 0
	v_pk_add_f32 v[26:27], v[58:59], v[26:27]
	v_pk_fma_f32 v[60:61], v[0:1], v[58:59], v[50:51] op_sel_hi:[0,1,1] neg_lo:[0,0,1] neg_hi:[0,0,1]
	v_pk_fma_f32 v[58:59], v[82:83], v[26:27], v[52:53] op_sel_hi:[0,1,1] neg_lo:[0,0,1] neg_hi:[0,0,1]
	v_pk_add_f32 v[26:27], v[26:27], v[28:29]
	v_cvt_pk_bf16_f32 v9, v60, v61
	v_pk_fma_f32 v[28:29], v[96:97], v[26:27], v[54:55] op_sel_hi:[0,1,1] neg_lo:[0,0,1] neg_hi:[0,0,1]
	v_cvt_pk_bf16_f32 v25, v28, v29
	v_pk_add_f32 v[28:29], v[90:91], v[46:47] neg_lo:[0,1] neg_hi:[0,1]
	v_cvt_pk_bf16_f32 v17, v58, v59
	v_pk_add_f32 v[26:27], v[26:27], v[28:29]
	v_max_i32_e32 v0, 4, v83
	v_pk_fma_f32 v[28:29], v[104:105], v[26:27], v[56:57] op_sel_hi:[0,1,1] neg_lo:[0,0,1] neg_hi:[0,0,1]
	v_cvt_pk_bf16_f32 v141, v28, v29
	v_pk_add_f32 v[28:29], v[36:37], v[48:49] neg_lo:[0,1] neg_hi:[0,1]
	global_store_dwordx4 v[30:31], v[6:9], off
	global_store_dwordx4 v[30:31], v[14:17], off offset:1024
	global_store_dwordx4 v[30:31], v[22:25], off offset:2048
	global_store_dwordx4 v[30:31], v[138:141], off offset:3072
	v_pk_add_f32 v[26:27], v[26:27], v[28:29]
	v_add_co_u32_e32 v6, vcc, 0x1000, v30
	v_pk_fma_f32 v[28:29], v[110:111], v[26:27], v[66:67] op_sel_hi:[0,1,1] neg_lo:[0,0,1] neg_hi:[0,0,1]
	v_cvt_pk_bf16_f32 v5, v28, v29
	v_pk_add_f32 v[28:29], v[114:115], v[50:51] neg_lo:[0,1] neg_hi:[0,1]
	v_addc_co_u32_e32 v7, vcc, 0, v31, vcc
	v_pk_add_f32 v[26:27], v[26:27], v[28:29]
	s_nop 0
	v_pk_fma_f32 v[28:29], v[116:117], v[26:27], v[78:79] op_sel_hi:[0,1,1] neg_lo:[0,0,1] neg_hi:[0,0,1]
	v_cvt_pk_bf16_f32 v13, v28, v29
	v_pk_add_f32 v[28:29], v[120:121], v[52:53] neg_lo:[0,1] neg_hi:[0,1]
	s_nop 0
	v_pk_add_f32 v[26:27], v[26:27], v[28:29]
	s_nop 0
	v_pk_fma_f32 v[28:29], v[126:127], v[26:27], v[90:91] op_sel_hi:[0,1,1] neg_lo:[0,0,1] neg_hi:[0,0,1]
	v_cvt_pk_bf16_f32 v21, v28, v29
	v_pk_add_f32 v[28:29], v[124:125], v[54:55] neg_lo:[0,1] neg_hi:[0,1]
	global_store_dwordx4 v[6:7], v[2:5], off
	global_store_dwordx4 v[6:7], v[10:13], off offset:1024
	global_store_dwordx4 v[6:7], v[18:21], off offset:2048
	v_pk_add_f32 v[2:3], v[26:27], v[28:29]

.LBB0_499:
	s_andn2_saveexec_b64 s[80:81], s[80:81]
	v_cmp_ne_u32_e32 vcc, 1, v6
	s_andn2_b64 s[0:1], s[0:1], exec
	s_and_b64 s[2:3], vcc, exec
	s_or_b64 s[0:1], s[0:1], s[2:3]
	s_mov_b64 s[74:75], exec
	s_or_b64 exec, exec, s[80:81]
	v_max_i32_e32 v6, 1, v167
	v_or_b32_e32 v129, 1, v167
	v_mov_b32_e32 v5, 11
	v_mov_b32_e32 v4, 4
	v_max_i32_e32 v183, 2, v167
	v_add_u32_e32 v195, -1, v6
	v_max_i32_e32 v194, 0, v129
	v_add_u32_e32 v113, 8, v167
	s_and_saveexec_b64 s[2:3], s[0:1]
	s_xor_b64 s[80:81], exec, s[2:3]
	s_cbranch_execz .LBB0_503
	v_max_i32_e32 v0, 8, v167
	v_add_u32_e32 v2, -8, v0
	v_min_u32_e32 v2, v2, v179
	v_mad_u64_u32 v[2:3], s[0:1], v2, s72, v[32:33]
	v_add_u32_e32 v250, -8, v167
	v_max_i32_e32 v250, 0, v250
	v_min_u32_e32 v250, v250, v179
	v_mad_u64_u32 v[250:251], s[98:99], v250, s72, v[32:33]
	global_load_dwordx4 v[226:229], v[250:251], off
	v_add_u32_e32 v250, -7, v167
	v_max_i32_e32 v250, 0, v250
	v_min_u32_e32 v250, v250, v179
	v_mad_u64_u32 v[250:251], s[98:99], v250, s72, v[32:33]
	global_load_dwordx4 v[230:233], v[250:251], off
	v_add_u32_e32 v250, -6, v167
	v_max_i32_e32 v250, 0, v250
	v_min_u32_e32 v250, v250, v179
	v_mad_u64_u32 v[250:251], s[98:99], v250, s72, v[32:33]
	global_load_dwordx4 v[234:237], v[250:251], off
	v_add_u32_e32 v250, -5, v167
	v_max_i32_e32 v250, 0, v250
	v_min_u32_e32 v250, v250, v179
	v_mad_u64_u32 v[250:251], s[98:99], v250, s72, v[32:33]
	global_load_dwordx4 v[238:241], v[250:251], off
	v_add_u32_e32 v250, -4, v167
	v_max_i32_e32 v250, 0, v250
	v_min_u32_e32 v250, v250, v179
	v_mad_u64_u32 v[250:251], s[98:99], v250, s72, v[32:33]
	global_load_dwordx4 v[242:245], v[250:251], off
	v_add_u32_e32 v250, -3, v167
	v_max_i32_e32 v250, 0, v250
	v_min_u32_e32 v250, v250, v179
	v_mad_u64_u32 v[250:251], s[98:99], v250, s72, v[32:33]
	global_load_dwordx4 v[246:249], v[250:251], off
	v_cmp_lt_i32_e32 vcc, 7, v167
	s_and_b64 vcc, vcc, s[4:5]
	v_or_b32_e32 v128, 2, v167
	v_or_b32_e32 v150, 3, v167
	v_or_b32_e32 v158, 4, v167
	v_or_b32_e32 v166, 5, v167
	v_or_b32_e32 v176, 6, v167
	v_or_b32_e32 v196, 7, v167
	v_add_u32_e32 v164, 9, v167
	v_max_i32_e32 v6, 0, v164
	v_min_u32_e32 v6, v6, v179
	v_add_u32_e32 v174, 10, v167
	v_add_u32_e32 v188, 11, v167
	v_add_u32_e32 v190, 12, v167
	v_add_u32_e32 v187, 13, v167
	v_add_u32_e32 v177, 14, v167
	s_andn2_b64 s[74:75], s[74:75], exec
	s_waitcnt vmcnt(5)
	v_cndmask_b32_e32 v13, 0, v226, vcc
	v_add_u32_e32 v2, -7, v167
	v_cmp_lt_i32_e64 s[0:1], v2, v131
	v_max_i32_e32 v2, 0, v2
	v_cndmask_b32_e32 v12, 0, v227, vcc
	v_cndmask_b32_e32 v11, 0, v228, vcc
	v_cndmask_b32_e32 v10, 0, v229, vcc
	v_add_u32_e32 v250, -2, v167
	v_max_i32_e32 v250, 0, v250
	v_min_u32_e32 v250, v250, v179
	v_mad_u64_u32 v[250:251], s[98:99], v250, s72, v[32:33]
	global_load_dwordx4 v[226:229], v[250:251], off
	v_cmp_lt_i32_e32 vcc, 6, v167
	v_min_u32_e32 v2, v2, v179
	s_and_b64 vcc, vcc, s[0:1]
	v_mad_u64_u32 v[2:3], s[0:1], v2, s72, v[32:33]
	v_lshlrev_b32_e32 v26, 16, v13
	v_and_b32_e32 v27, 0xffff0000, v13
	v_lshlrev_b32_e32 v104, 16, v12
	v_and_b32_e32 v105, 0xffff0000, v12
	v_lshlrev_b32_e32 v28, 16, v11
	v_and_b32_e32 v29, 0xffff0000, v11
	v_lshlrev_b32_e32 v58, 16, v10
	v_and_b32_e32 v59, 0xffff0000, v10
	s_waitcnt vmcnt(5)
	v_cndmask_b32_e32 v15, 0, v230, vcc
	v_add_u32_e32 v2, -6, v167
	v_cmp_lt_i32_e64 s[0:1], v2, v131
	v_max_i32_e32 v2, 0, v2
	v_cndmask_b32_e32 v16, 0, v231, vcc
	v_cndmask_b32_e32 v17, 0, v232, vcc
	v_cndmask_b32_e32 v18, 0, v233, vcc
	v_add_u32_e32 v250, -1, v167
	v_max_i32_e32 v250, 0, v250
	v_min_u32_e32 v250, v250, v179
	v_mad_u64_u32 v[250:251], s[98:99], v250, s72, v[32:33]
	global_load_dwordx4 v[230:233], v[250:251], off
	v_cmp_lt_i32_e32 vcc, 5, v167
	v_min_u32_e32 v2, v2, v179
	s_and_b64 vcc, vcc, s[0:1]
	v_mad_u64_u32 v[2:3], s[0:1], v2, s72, v[32:33]
	v_lshlrev_b32_e32 v14, 16, v15
	v_and_b32_e32 v15, 0xffff0000, v15
	v_lshlrev_b32_e32 v52, 16, v18
	v_and_b32_e32 v53, 0xffff0000, v18
	v_lshlrev_b32_e32 v98, 16, v16
	v_and_b32_e32 v99, 0xffff0000, v16
	v_lshlrev_b32_e32 v16, 16, v17
	v_and_b32_e32 v17, 0xffff0000, v17
	s_waitcnt vmcnt(5)
	v_cndmask_b32_e32 v19, 0, v234, vcc
	v_add_u32_e32 v2, -5, v167
	v_cmp_lt_i32_e64 s[0:1], v2, v131
	v_max_i32_e32 v2, 0, v2
	v_cndmask_b32_e32 v20, 0, v235, vcc
	v_cndmask_b32_e32 v21, 0, v236, vcc
	v_cndmask_b32_e32 v22, 0, v237, vcc
	v_add_u32_e32 v250, 0, v167
	v_max_i32_e32 v250, 0, v250
	v_min_u32_e32 v250, v250, v179
	v_mad_u64_u32 v[250:251], s[98:99], v250, s72, v[32:33]
	global_load_dwordx4 v[234:237], v[250:251], off
	v_cmp_lt_i32_e32 vcc, 4, v167
	v_min_u32_e32 v2, v2, v179
	s_and_b64 vcc, vcc, s[0:1]
	v_mad_u64_u32 v[2:3], s[0:1], v2, s72, v[32:33]
	v_lshlrev_b32_e32 v18, 16, v19
	v_and_b32_e32 v19, 0xffff0000, v19
	v_lshlrev_b32_e32 v54, 16, v22
	v_and_b32_e32 v55, 0xffff0000, v22
	v_lshlrev_b32_e32 v100, 16, v20
	v_and_b32_e32 v101, 0xffff0000, v20
	v_lshlrev_b32_e32 v20, 16, v21
	v_and_b32_e32 v21, 0xffff0000, v21
	s_waitcnt vmcnt(5)
	v_cndmask_b32_e32 v23, 0, v238, vcc
	v_max_i32_e32 v2, 4, v167
	v_add_u32_e32 v2, -4, v2
	v_min_u32_e32 v2, v2, v179
	v_cndmask_b32_e32 v24, 0, v239, vcc
	v_mad_u64_u32 v[2:3], s[0:1], v2, s72, v[32:33]
	v_cndmask_b32_e32 v25, 0, v240, vcc
	v_cndmask_b32_e32 v34, 0, v241, vcc
	v_add_u32_e32 v250, 1, v167
	v_max_i32_e32 v250, 0, v250
	v_min_u32_e32 v250, v250, v179
	v_mad_u64_u32 v[250:251], s[98:99], v250, s72, v[32:33]
	global_load_dwordx4 v[238:241], v[250:251], off
	v_cmp_lt_i32_e32 vcc, 3, v167
	s_and_b64 vcc, vcc, s[4:5]
	v_lshlrev_b32_e32 v56, 16, v34
	v_and_b32_e32 v57, 0xffff0000, v34
	v_lshlrev_b32_e32 v22, 16, v23
	v_and_b32_e32 v23, 0xffff0000, v23
	v_lshlrev_b32_e32 v102, 16, v24
	v_and_b32_e32 v103, 0xffff0000, v24
	v_lshlrev_b32_e32 v24, 16, v25
	v_and_b32_e32 v25, 0xffff0000, v25
	s_waitcnt vmcnt(5)
	v_cndmask_b32_e32 v38, 0, v242, vcc
	v_add_u32_e32 v2, -3, v167
	v_cmp_lt_i32_e64 s[0:1], v2, v131
	v_max_i32_e32 v2, 0, v2
	v_cndmask_b32_e32 v37, 0, v243, vcc
	v_cndmask_b32_e32 v36, 0, v244, vcc
	v_cndmask_b32_e32 v35, 0, v245, vcc
	v_add_u32_e32 v250, 2, v167
	v_max_i32_e32 v250, 0, v250
	v_min_u32_e32 v250, v250, v179
	v_mad_u64_u32 v[250:251], s[98:99], v250, s72, v[32:33]
	global_load_dwordx4 v[242:245], v[250:251], off
	v_cmp_lt_i32_e32 vcc, 2, v167
	v_min_u32_e32 v2, v2, v179
	s_and_b64 vcc, vcc, s[0:1]
	v_mad_u64_u32 v[2:3], s[0:1], v2, s72, v[32:33]
	v_lshlrev_b32_e32 v44, 16, v37
	v_and_b32_e32 v45, 0xffff0000, v37
	v_lshlrev_b32_e32 v46, 16, v35
	v_and_b32_e32 v47, 0xffff0000, v35
	s_waitcnt vmcnt(5)
	v_cndmask_b32_e32 v42, 0, v246, vcc
	v_add_u32_e32 v2, -2, v183
	v_min_u32_e32 v2, v2, v179
	v_cndmask_b32_e32 v41, 0, v247, vcc
	v_mad_u64_u32 v[2:3], s[0:1], v2, s72, v[32:33]
	v_cndmask_b32_e32 v40, 0, v248, vcc
	v_cndmask_b32_e32 v39, 0, v249, vcc
	v_add_u32_e32 v250, 3, v167
	v_max_i32_e32 v250, 0, v250
	v_min_u32_e32 v250, v250, v179
	v_mad_u64_u32 v[250:251], s[98:99], v250, s72, v[32:33]
	global_load_dwordx4 v[246:249], v[250:251], off
	v_cmp_lt_i32_e32 vcc, 1, v167
	s_and_b64 vcc, vcc, s[4:5]
	v_lshlrev_b32_e32 v94, 16, v41
	v_and_b32_e32 v95, 0xffff0000, v41
	v_lshlrev_b32_e32 v12, 16, v40
	v_and_b32_e32 v13, 0xffff0000, v40
	v_lshlrev_b32_e32 v48, 16, v39
	v_and_b32_e32 v49, 0xffff0000, v39
	v_lshlrev_b32_e32 v10, 16, v42
	v_and_b32_e32 v11, 0xffff0000, v42
	s_waitcnt vmcnt(5)
	v_cndmask_b32_e32 v43, 0, v226, vcc
	v_min_u32_e32 v2, v195, v179
	v_cndmask_b32_e32 v60, 0, v227, vcc
	v_mad_u64_u32 v[2:3], s[0:1], v2, s72, v[32:33]
	v_cndmask_b32_e32 v50, 0, v228, vcc
	v_cndmask_b32_e32 v51, 0, v229, vcc
	v_add_u32_e32 v250, 4, v167
	v_max_i32_e32 v250, 0, v250
	v_min_u32_e32 v250, v250, v179
	v_mad_u64_u32 v[250:251], s[98:99], v250, s72, v[32:33]
	global_load_dwordx4 v[226:229], v[250:251], off
	v_cmp_lt_i32_e32 vcc, 0, v167
	s_and_b64 vcc, vcc, s[4:5]
	v_cmp_lt_i32_e64 s[0:1], v167, v131
	v_lshlrev_b32_e32 v96, 16, v60
	v_and_b32_e32 v97, 0xffff0000, v60
	v_lshlrev_b32_e32 v42, 16, v43
	v_and_b32_e32 v43, 0xffff0000, v43
	v_lshlrev_b32_e32 v76, 16, v50
	v_and_b32_e32 v77, 0xffff0000, v50
	v_lshlrev_b32_e32 v50, 16, v51
	v_and_b32_e32 v51, 0xffff0000, v51
	s_waitcnt vmcnt(5)
	v_cndmask_b32_e32 v64, 0, v230, vcc
	v_max_i32_e32 v2, 0, v167
	v_cndmask_b32_e32 v63, 0, v231, vcc
	v_cndmask_b32_e32 v62, 0, v232, vcc
	v_cndmask_b32_e32 v61, 0, v233, vcc
	v_add_u32_e32 v250, 5, v167
	v_max_i32_e32 v250, 0, v250
	v_min_u32_e32 v250, v250, v179
	v_mad_u64_u32 v[250:251], s[98:99], v250, s72, v[32:33]
	global_load_dwordx4 v[230:233], v[250:251], off
	v_cmp_lt_i32_e32 vcc, -1, v181
	v_min_u32_e32 v2, v2, v179
	s_and_b64 vcc, vcc, s[0:1]
	v_mad_u64_u32 v[2:3], s[0:1], v2, s72, v[32:33]
	v_cmp_lt_i32_e64 s[0:1], v129, v131
	v_lshlrev_b32_e32 v134, 16, v64
	v_and_b32_e32 v135, 0xffff0000, v64
	v_lshlrev_b32_e32 v110, 16, v63
	v_and_b32_e32 v111, 0xffff0000, v63
	v_lshlrev_b32_e32 v80, 16, v62
	v_and_b32_e32 v81, 0xffff0000, v62
	v_lshlrev_b32_e32 v62, 16, v61
	v_and_b32_e32 v63, 0xffff0000, v61
	s_waitcnt vmcnt(5)
	v_cndmask_b32_e32 v68, 0, v234, vcc
	v_cndmask_b32_e32 v67, 0, v235, vcc
	v_cndmask_b32_e32 v66, 0, v236, vcc
	v_cndmask_b32_e32 v65, 0, v237, vcc
	v_add_u32_e32 v250, 6, v167
	v_max_i32_e32 v250, 0, v250
	v_min_u32_e32 v250, v250, v179
	v_mad_u64_u32 v[250:251], s[98:99], v250, s72, v[32:33]
	global_load_dwordx4 v[234:237], v[250:251], off
	v_cmp_lt_i32_e32 vcc, -2, v167
	v_min_u32_e32 v2, v194, v179
	s_and_b64 vcc, vcc, s[0:1]
	v_mad_u64_u32 v[2:3], s[0:1], v2, s72, v[32:33]
	v_cmp_lt_i32_e64 s[0:1], v128, v131
	v_lshlrev_b32_e32 v108, 16, v67
	v_and_b32_e32 v109, 0xffff0000, v67
	v_lshlrev_b32_e32 v78, 16, v66
	v_and_b32_e32 v79, 0xffff0000, v66
	v_lshlrev_b32_e32 v132, 16, v68
	v_and_b32_e32 v133, 0xffff0000, v68
	v_lshlrev_b32_e32 v60, 16, v65
	v_and_b32_e32 v61, 0xffff0000, v65
	s_waitcnt vmcnt(5)
	v_cndmask_b32_e32 v72, 0, v238, vcc
	v_max_i32_e32 v2, 0, v128
	v_cndmask_b32_e32 v71, 0, v239, vcc
	v_cndmask_b32_e32 v70, 0, v240, vcc
	v_cndmask_b32_e32 v69, 0, v241, vcc
	v_add_u32_e32 v250, 7, v167
	v_max_i32_e32 v250, 0, v250
	v_min_u32_e32 v250, v250, v179
	v_mad_u64_u32 v[250:251], s[98:99], v250, s72, v[32:33]
	global_load_dwordx4 v[238:241], v[250:251], off
	v_cmp_lt_i32_e32 vcc, -3, v167
	v_min_u32_e32 v2, v2, v179
	s_and_b64 vcc, vcc, s[0:1]
	v_mad_u64_u32 v[2:3], s[0:1], v2, s72, v[32:33]
	v_cmp_lt_i32_e64 s[0:1], v150, v131
	v_lshlrev_b32_e32 v136, 16, v72
	v_and_b32_e32 v137, 0xffff0000, v72
	v_lshlrev_b32_e32 v114, 16, v71
	v_and_b32_e32 v115, 0xffff0000, v71
	v_lshlrev_b32_e32 v82, 16, v70
	v_and_b32_e32 v83, 0xffff0000, v70
	v_lshlrev_b32_e32 v64, 16, v69
	v_and_b32_e32 v65, 0xffff0000, v69
	v_max_i32_e32 v128, 8, v128
	s_waitcnt vmcnt(5)
	v_cndmask_b32_e32 v84, 0, v242, vcc
	v_max_i32_e32 v2, 0, v150
	v_cndmask_b32_e32 v75, 0, v243, vcc
	v_cndmask_b32_e32 v74, 0, v244, vcc
	v_cndmask_b32_e32 v73, 0, v245, vcc
	v_add_u32_e32 v250, 8, v167
	v_max_i32_e32 v250, 0, v250
	v_min_u32_e32 v250, v250, v179
	v_mad_u64_u32 v[250:251], s[98:99], v250, s72, v[32:33]
	global_load_dwordx4 v[242:245], v[250:251], off
	v_cmp_lt_i32_e32 vcc, -4, v167
	v_min_u32_e32 v2, v2, v179
	s_and_b64 vcc, vcc, s[0:1]
	v_mad_u64_u32 v[2:3], s[0:1], v2, s72, v[32:33]
	v_cmp_lt_i32_e64 s[0:1], v158, v131
	v_lshlrev_b32_e32 v66, 16, v73
	v_and_b32_e32 v67, 0xffff0000, v73
	v_lshlrev_b32_e32 v138, 16, v84
	v_and_b32_e32 v139, 0xffff0000, v84
	v_lshlrev_b32_e32 v116, 16, v75
	v_and_b32_e32 v117, 0xffff0000, v75
	v_lshlrev_b32_e32 v84, 16, v74
	v_and_b32_e32 v85, 0xffff0000, v74
	v_max_i32_e32 v150, 8, v150
	s_waitcnt vmcnt(5)
	v_cndmask_b32_e32 v89, 0, v246, vcc
	v_max_i32_e32 v2, 0, v158
	v_cndmask_b32_e32 v86, 0, v247, vcc
	v_cndmask_b32_e32 v87, 0, v248, vcc
	v_cndmask_b32_e32 v88, 0, v249, vcc
	v_add_u32_e32 v250, 9, v167
	v_max_i32_e32 v250, 0, v250
	v_min_u32_e32 v250, v250, v179
	v_mad_u64_u32 v[250:251], s[98:99], v250, s72, v[32:33]
	global_load_dwordx4 v[246:249], v[250:251], off
	v_cmp_lt_i32_e32 vcc, -5, v167
	v_min_u32_e32 v2, v2, v179
	s_and_b64 vcc, vcc, s[0:1]
	v_mad_u64_u32 v[2:3], s[0:1], v2, s72, v[32:33]
	v_cmp_lt_i32_e64 s[0:1], v166, v131
	v_lshlrev_b32_e32 v140, 16, v89
	v_and_b32_e32 v141, 0xffff0000, v89
	v_lshlrev_b32_e32 v68, 16, v88
	v_and_b32_e32 v69, 0xffff0000, v88
	v_max_i32_e32 v158, 8, v158
	v_lshlrev_b32_e32 v118, 16, v86
	v_and_b32_e32 v119, 0xffff0000, v86
	v_lshlrev_b32_e32 v86, 16, v87
	v_and_b32_e32 v87, 0xffff0000, v87
	s_waitcnt vmcnt(5)
	v_cndmask_b32_e32 v93, 0, v226, vcc
	v_max_i32_e32 v2, 0, v166
	v_cndmask_b32_e32 v92, 0, v227, vcc
	v_cndmask_b32_e32 v91, 0, v228, vcc
	v_cndmask_b32_e32 v90, 0, v229, vcc
	v_add_u32_e32 v250, 10, v167
	v_max_i32_e32 v250, 0, v250
	v_min_u32_e32 v250, v250, v179
	v_mad_u64_u32 v[250:251], s[98:99], v250, s72, v[32:33]
	global_load_dwordx4 v[226:229], v[250:251], off
	v_cmp_lt_i32_e32 vcc, -6, v167
	v_min_u32_e32 v2, v2, v179
	s_and_b64 vcc, vcc, s[0:1]
	v_mad_u64_u32 v[2:3], s[0:1], v2, s72, v[32:33]
	v_cmp_lt_i32_e64 s[0:1], v176, v131
	v_lshlrev_b32_e32 v88, 16, v91
	v_and_b32_e32 v89, 0xffff0000, v91
	v_lshlrev_b32_e32 v70, 16, v90
	v_and_b32_e32 v71, 0xffff0000, v90
	v_lshlrev_b32_e32 v144, 16, v93
	v_and_b32_e32 v145, 0xffff0000, v93
	v_lshlrev_b32_e32 v120, 16, v92
	v_and_b32_e32 v121, 0xffff0000, v92
	v_max_i32_e32 v166, 8, v166
	s_waitcnt vmcnt(5)
	v_cndmask_b32_e32 v122, 0, v230, vcc
	v_max_i32_e32 v2, 0, v176
	v_cndmask_b32_e32 v112, 0, v231, vcc
	v_cndmask_b32_e32 v107, 0, v232, vcc
	v_cndmask_b32_e32 v106, 0, v233, vcc
	v_add_u32_e32 v250, 11, v167
	v_max_i32_e32 v250, 0, v250
	v_min_u32_e32 v250, v250, v179
	v_mad_u64_u32 v[250:251], s[98:99], v250, s72, v[32:33]
	global_load_dwordx4 v[230:233], v[250:251], off
	v_cmp_lt_i32_e32 vcc, -7, v167
	v_min_u32_e32 v2, v2, v179
	s_and_b64 vcc, vcc, s[0:1]
	v_mad_u64_u32 v[2:3], s[0:1], v2, s72, v[32:33]
	v_cmp_lt_i32_e64 s[0:1], v196, v131
	v_lshlrev_b32_e32 v72, 16, v106
	v_and_b32_e32 v73, 0xffff0000, v106
	v_min_i32_e32 v106, v113, v131
	v_sub_u32_e32 v0, v106, v0
	v_add_u32_e32 v0, 8, v0
	v_cvt_f32_i32_e32 v0, v0
	v_lshlrev_b32_e32 v90, 16, v107
	v_and_b32_e32 v91, 0xffff0000, v107
	v_lshlrev_b32_e32 v146, 16, v122
	v_and_b32_e32 v147, 0xffff0000, v122
	v_lshlrev_b32_e32 v122, 16, v112
	v_and_b32_e32 v123, 0xffff0000, v112
	v_max_i32_e32 v176, 8, v176
	s_waitcnt vmcnt(5)
	v_cndmask_b32_e32 v124, 0, v234, vcc
	v_max_i32_e32 v2, 0, v196
	v_cndmask_b32_e32 v125, 0, v235, vcc
	v_cndmask_b32_e32 v155, 0, v236, vcc
	v_cndmask_b32_e32 v154, 0, v237, vcc
	v_add_u32_e32 v250, 12, v167
	v_max_i32_e32 v250, 0, v250
	v_min_u32_e32 v250, v250, v179
	v_mad_u64_u32 v[250:251], s[98:99], v250, s72, v[32:33]
	global_load_dwordx4 v[234:237], v[250:251], off
	v_cmp_lt_i32_e32 vcc, -8, v167
	v_min_u32_e32 v2, v2, v179
	s_and_b64 vcc, vcc, s[0:1]
	v_mad_u64_u32 v[2:3], s[0:1], v2, s72, v[32:33]
	v_lshlrev_b32_e32 v74, 16, v154
	v_and_b32_e32 v75, 0xffff0000, v154
	v_lshlrev_b32_e32 v92, 16, v155
	v_and_b32_e32 v93, 0xffff0000, v155
	v_lshlrev_b32_e32 v148, 16, v124
	v_and_b32_e32 v149, 0xffff0000, v124
	v_lshlrev_b32_e32 v124, 16, v125
	v_and_b32_e32 v125, 0xffff0000, v125
	s_waitcnt vmcnt(5)
	v_cndmask_b32_e32 v185, 0, v238, vcc
	v_max_i32_e32 v2, 0, v113
	v_min_u32_e32 v2, v2, v179
	v_cndmask_b32_e32 v184, 0, v239, vcc
	v_mad_u64_u32 v[2:3], s[0:1], v2, s72, v[32:33]
	v_cndmask_b32_e32 v175, 0, v240, vcc
	v_cndmask_b32_e32 v165, 0, v241, vcc
	v_add_u32_e32 v250, 13, v167
	v_max_i32_e32 v250, 0, v250
	v_min_u32_e32 v250, v250, v179
	v_mad_u64_u32 v[250:251], s[98:99], v250, s72, v[32:33]
	global_load_dwordx4 v[238:241], v[250:251], off
	v_cmp_lt_i32_e32 vcc, -10, v167
	v_cmp_lt_i32_e64 s[0:1], v164, v131
	s_and_b64 vcc, vcc, s[0:1]
	v_mad_u64_u32 v[6:7], s[0:1], v6, s72, v[32:33]
	v_cmp_lt_i32_e64 s[0:1], v174, v131
	v_min_i32_e32 v164, v164, v131
	v_and_b32_e32 v37, 0xffff0000, v165
	v_lshlrev_b32_e32 v40, 16, v175
	v_and_b32_e32 v41, 0xffff0000, v175
	v_lshlrev_b32_e32 v34, 16, v185
	v_and_b32_e32 v35, 0xffff0000, v185
	v_and_b32_e32 v39, 0xffff0000, v184
	s_waitcnt vmcnt(4)
	v_cndmask_b32_e32 v153, 0, v246, vcc
	v_max_i32_e32 v6, 0, v174
	v_cndmask_b32_e32 v152, 0, v247, vcc
	v_cndmask_b32_e32 v126, 0, v248, vcc
	v_cndmask_b32_e32 v127, 0, v249, vcc
	v_add_u32_e32 v250, 14, v167
	v_max_i32_e32 v250, 0, v250
	v_min_u32_e32 v250, v250, v179
	v_mad_u64_u32 v[250:251], s[98:99], v250, s72, v[32:33]
	global_load_dwordx4 v[246:249], v[250:251], off
	v_cmp_lt_i32_e32 vcc, -11, v167
	v_min_u32_e32 v6, v6, v179
	s_and_b64 vcc, vcc, s[0:1]
	v_mad_u64_u32 v[6:7], s[0:1], v6, s72, v[32:33]
	v_cmp_lt_i32_e64 s[0:1], v188, v131
	v_min_i32_e32 v174, v174, v131
	v_sub_u32_e32 v128, v174, v128
	v_add_u32_e32 v128, 8, v128
	v_cvt_f32_i32_e32 v128, v128
	v_and_b32_e32 v185, 0xffff0000, v153
	s_waitcnt vmcnt(4)
	v_cndmask_b32_e32 v163, 0, v226, vcc
	v_max_i32_e32 v6, 0, v188
	v_cndmask_b32_e32 v162, 0, v227, vcc
	v_cndmask_b32_e32 v142, 0, v228, vcc
	v_cndmask_b32_e32 v143, 0, v229, vcc
	v_cmp_lt_i32_e32 vcc, -12, v167
	v_min_u32_e32 v6, v6, v179
	s_and_b64 vcc, vcc, s[0:1]
	v_mad_u64_u32 v[6:7], s[0:1], v6, s72, v[32:33]
	v_cmp_lt_i32_e64 s[0:1], v190, v131
	v_lshlrev_b32_e32 v192, 16, v163
	v_and_b32_e32 v193, 0xffff0000, v163
	v_pk_add_f32 v[192:193], v[192:193], v[18:19] neg_lo:[0,1] neg_hi:[0,1]
	v_and_b32_e32 v163, 0xffff0000, v142
	s_waitcnt vmcnt(3)
	v_cndmask_b32_e32 v171, 0, v230, vcc
	v_max_i32_e32 v6, 0, v190
	v_cndmask_b32_e32 v170, 0, v231, vcc
	v_cndmask_b32_e32 v156, 0, v232, vcc
	v_cndmask_b32_e32 v157, 0, v233, vcc
	v_cmp_lt_i32_e32 vcc, -13, v167
	v_min_u32_e32 v6, v6, v179
	s_and_b64 vcc, vcc, s[0:1]
	v_mad_u64_u32 v[6:7], s[0:1], v6, s72, v[32:33]
	v_cmp_lt_i32_e64 s[0:1], v187, v131
	v_lshlrev_b32_e32 v208, 16, v171
	v_and_b32_e32 v209, 0xffff0000, v171
	v_pk_add_f32 v[208:209], v[208:209], v[22:23] neg_lo:[0,1] neg_hi:[0,1]
	v_and_b32_e32 v171, 0xffff0000, v156
	s_waitcnt vmcnt(2)
	v_cndmask_b32_e32 v173, 0, v234, vcc
	v_max_i32_e32 v6, 0, v187
	v_cndmask_b32_e32 v172, 0, v235, vcc
	v_cndmask_b32_e32 v160, 0, v236, vcc
	v_cndmask_b32_e32 v161, 0, v237, vcc
	v_cmp_lt_i32_e32 vcc, -14, v167
	v_min_u32_e32 v6, v6, v179
	s_and_b64 vcc, vcc, s[0:1]
	v_mad_u64_u32 v[6:7], s[0:1], v6, s72, v[32:33]
	v_cmp_lt_i32_e64 s[0:1], v177, v131
	v_and_b32_e32 v211, 0xffff0000, v173
	s_waitcnt vmcnt(1)
	v_cndmask_b32_e32 v186, 0, v238, vcc
	v_max_i32_e32 v6, 0, v177
	v_cndmask_b32_e32 v178, 0, v239, vcc
	v_cndmask_b32_e32 v168, 0, v240, vcc
	v_cndmask_b32_e32 v169, 0, v241, vcc
	v_cmp_lt_i32_e32 vcc, -15, v167
	v_min_u32_e32 v6, v6, v179
	s_and_b64 vcc, vcc, s[0:1]
	v_mad_u64_u32 v[6:7], s[0:1], v6, s72, v[32:33]
	v_div_scale_f32 v106, s[0:1], v0, v0, 1.0
	v_rcp_f32_e32 v107, v106
	v_cmp_lt_i32_e64 s[0:1], v113, v131
	v_min_i32_e32 v177, v177, v131
	v_sub_u32_e32 v176, v177, v176
	v_fma_f32 v112, -v106, v107, 1.0
	v_fmac_f32_e32 v107, v112, v107
	v_add_u32_e32 v176, 8, v176
	v_cvt_f32_i32_e32 v176, v176
	v_lshlrev_b32_e32 v214, 16, v178
	v_and_b32_e32 v215, 0xffff0000, v178
	s_waitcnt vmcnt(0)
	v_cndmask_b32_e32 v220, 0, v246, vcc
	v_cndmask_b32_e32 v199, 0, v247, vcc
	v_cndmask_b32_e32 v198, 0, v248, vcc
	v_cndmask_b32_e32 v197, 0, v249, vcc
	v_div_scale_f32 v112, vcc, 1.0, v0, 1.0
	v_mul_f32_e32 v154, v112, v107
	v_fma_f32 v155, -v106, v154, v112
	v_fmac_f32_e32 v154, v155, v107
	v_fma_f32 v106, -v106, v154, v112
	v_max_i32_e32 v112, 8, v129
	v_sub_u32_e32 v112, v164, v112
	v_add_u32_e32 v112, 8, v112
	v_cvt_f32_i32_e32 v112, v112
	v_div_fmas_f32 v106, v106, v107, v154
	v_cmp_lt_i32_e32 vcc, -9, v167
	s_and_b64 vcc, vcc, s[0:1]
	v_div_scale_f32 v164, s[0:1], v112, v112, 1.0
	v_lshlrev_b32_e32 v8, 16, v36
	v_and_b32_e32 v9, 0xffff0000, v36
	v_lshlrev_b32_e32 v36, 16, v165
	v_rcp_f32_e32 v165, v164
	v_cndmask_b32_e32 v107, 0, v245, vcc
	v_cndmask_b32_e32 v5, 0, v244, vcc
	v_cndmask_b32_e32 v4, 0, v243, vcc
	v_fma_f32 v175, -v164, v165, 1.0
	v_cndmask_b32_e32 v3, 0, v242, vcc
	v_fmac_f32_e32 v165, v175, v165
	v_div_scale_f32 v175, vcc, 1.0, v112, 1.0
	v_mul_f32_e32 v180, v175, v165
	v_fma_f32 v182, -v164, v180, v175
	v_fmac_f32_e32 v180, v182, v165
	v_div_scale_f32 v174, s[0:1], v128, v128, 1.0
	v_fma_f32 v164, -v164, v180, v175
	v_rcp_f32_e32 v175, v174
	v_div_fmas_f32 v164, v164, v165, v180
	v_lshlrev_b32_e32 v6, 16, v38
	v_and_b32_e32 v7, 0xffff0000, v38
	v_fma_f32 v180, -v174, v175, 1.0
	v_fmac_f32_e32 v175, v180, v175
	v_div_scale_f32 v180, vcc, 1.0, v128, 1.0
	v_mul_f32_e32 v182, v180, v175
	v_fma_f32 v189, -v174, v182, v180
	v_fmac_f32_e32 v182, v189, v175
	v_fma_f32 v174, -v174, v182, v180
	v_min_i32_e32 v180, v188, v131
	v_sub_u32_e32 v150, v180, v150
	v_add_u32_e32 v150, 8, v150
	v_cvt_f32_i32_e32 v150, v150
	v_div_fmas_f32 v174, v174, v175, v182
	v_lshlrev_b32_e32 v38, 16, v184
	v_lshlrev_b32_e32 v184, 16, v153
	v_div_scale_f32 v180, s[0:1], v150, v150, 1.0
	v_rcp_f32_e32 v182, v180
	v_lshlrev_b32_e32 v222, 16, v220
	v_and_b32_e32 v223, 0xffff0000, v220
	v_pk_add_f32 v[220:221], v[26:27], 0 op_sel_hi:[1,0]
	v_fma_f32 v188, -v180, v182, 1.0
	v_fmac_f32_e32 v182, v188, v182
	v_div_scale_f32 v188, vcc, 1.0, v150, 1.0
	v_mul_f32_e32 v189, v188, v182
	v_fma_f32 v191, -v180, v189, v188
	v_fmac_f32_e32 v189, v191, v182
	v_fma_f32 v180, -v180, v189, v188
	v_div_fmas_f32 v180, v180, v182, v189
	v_div_fixup_f32 v150, v180, v150, 1.0
	v_min_i32_e32 v180, v190, v131
	v_sub_u32_e32 v158, v180, v158
	v_add_u32_e32 v158, 8, v158
	v_cvt_f32_i32_e32 v158, v158
	v_pk_add_f32 v[184:185], v[184:185], v[14:15] neg_lo:[0,1] neg_hi:[0,1]
	v_pk_add_f32 v[14:15], v[220:221], v[14:15]
	v_lshlrev_b32_e32 v2, 16, v3
	v_div_scale_f32 v180, s[0:1], v158, v158, 1.0
	v_rcp_f32_e32 v182, v180
	v_pk_add_f32 v[14:15], v[14:15], v[18:19]
	v_and_b32_e32 v3, 0xffff0000, v3
	v_pk_add_f32 v[14:15], v[14:15], v[22:23]
	v_fma_f32 v190, -v180, v182, 1.0
	v_pk_add_f32 v[14:15], v[14:15], v[6:7]
	v_fmac_f32_e32 v182, v190, v182
	v_div_scale_f32 v190, vcc, 1.0, v158, 1.0
	v_pk_add_f32 v[14:15], v[14:15], v[10:11]
	v_mul_f32_e32 v191, v190, v182
	v_pk_add_f32 v[14:15], v[14:15], v[42:43]
	v_fma_f32 v210, -v180, v191, v190
	v_pk_add_f32 v[14:15], v[14:15], v[134:135]
	v_fmac_f32_e32 v191, v210, v182
	v_pk_add_f32 v[14:15], v[14:15], v[132:133]
	v_fma_f32 v180, -v180, v191, v190
	v_pk_add_f32 v[14:15], v[14:15], v[136:137]
	v_div_fmas_f32 v180, v180, v182, v191
	v_pk_add_f32 v[14:15], v[14:15], v[138:139]
	v_div_fixup_f32 v158, v180, v158, 1.0
	v_min_i32_e32 v180, v187, v131
	v_pk_add_f32 v[14:15], v[14:15], v[140:141]
	v_sub_u32_e32 v166, v180, v166
	v_pk_add_f32 v[14:15], v[14:15], v[144:145]
	v_add_u32_e32 v166, 8, v166
	v_pk_add_f32 v[14:15], v[14:15], v[146:147]
	v_cvt_f32_i32_e32 v166, v166
	v_pk_add_f32 v[14:15], v[14:15], v[148:149]
	v_pk_add_f32 v[2:3], v[2:3], v[26:27] neg_lo:[0,1] neg_hi:[0,1]
	v_pk_add_f32 v[14:15], v[14:15], v[34:35]
	v_div_fixup_f32 v0, v106, v0, 1.0
	v_div_fixup_f32 v112, v164, v112, 1.0
	v_lshlrev_b32_e32 v164, 16, v152
	v_and_b32_e32 v165, 0xffff0000, v152
	v_pk_add_f32 v[2:3], v[14:15], v[2:3]
	v_pk_add_f32 v[134:135], v[104:105], 0 op_sel_hi:[1,0]
	v_pk_fma_f32 v[18:19], v[0:1], v[14:15], v[132:133] op_sel_hi:[0,1,1] neg_lo:[0,0,1] neg_hi:[0,0,1]
	v_pk_fma_f32 v[14:15], v[112:113], v[2:3], v[136:137] op_sel_hi:[0,1,1] neg_lo:[0,0,1] neg_hi:[0,0,1]
	v_pk_add_f32 v[136:137], v[164:165], v[98:99] neg_lo:[0,1] neg_hi:[0,1]
	v_pk_add_f32 v[98:99], v[134:135], v[98:99]
	v_div_scale_f32 v180, s[0:1], v166, v166, 1.0
	v_pk_add_f32 v[98:99], v[98:99], v[100:101]
	v_rcp_f32_e32 v182, v180
	v_pk_add_f32 v[98:99], v[98:99], v[102:103]
	v_div_scale_f32 v177, s[0:1], v176, v176, 1.0
	v_pk_add_f32 v[98:99], v[98:99], v[44:45]
	v_fma_f32 v187, -v180, v182, 1.0
	v_pk_add_f32 v[98:99], v[98:99], v[94:95]
	v_fmac_f32_e32 v182, v187, v182
	v_pk_add_f32 v[98:99], v[98:99], v[96:97]
	v_div_scale_f32 v187, vcc, 1.0, v166, 1.0
	v_pk_add_f32 v[98:99], v[98:99], v[110:111]
	v_mul_f32_e32 v212, v187, v182
	v_pk_add_f32 v[98:99], v[98:99], v[108:109]
	v_fma_f32 v213, -v180, v212, v187
	v_pk_add_f32 v[98:99], v[98:99], v[114:115]
	v_rcp_f32_e32 v178, v177
	v_pk_add_f32 v[98:99], v[98:99], v[116:117]
	v_fmac_f32_e32 v212, v213, v182
	v_pk_add_f32 v[98:99], v[98:99], v[118:119]
	v_fma_f32 v180, -v180, v212, v187
	v_pk_add_f32 v[98:99], v[98:99], v[120:121]
	v_div_fmas_f32 v180, v180, v182, v212
	v_pk_add_f32 v[98:99], v[98:99], v[122:123]
	v_lshlrev_b32_e32 v154, 16, v4
	v_and_b32_e32 v155, 0xffff0000, v4
	v_div_fixup_f32 v166, v180, v166, 1.0
	v_fma_f32 v180, -v177, v178, 1.0
	v_pk_add_f32 v[98:99], v[98:99], v[124:125]
	v_div_fixup_f32 v128, v174, v128, 1.0
	v_lshlrev_b32_e32 v174, 16, v162
	v_and_b32_e32 v175, 0xffff0000, v162
	v_fmac_f32_e32 v178, v180, v178
	v_div_scale_f32 v180, vcc, 1.0, v176, 1.0
	v_pk_add_f32 v[2:3], v[2:3], v[184:185]
	v_pk_add_f32 v[104:105], v[154:155], v[104:105] neg_lo:[0,1] neg_hi:[0,1]
	v_pk_add_f32 v[98:99], v[98:99], v[38:39]
	v_mul_f32_e32 v182, v180, v178
	v_cvt_pk_bf16_f32 v22, v14, v15
	v_pk_fma_f32 v[14:15], v[128:129], v[2:3], v[138:139] op_sel_hi:[0,1,1] neg_lo:[0,0,1] neg_hi:[0,0,1]
	v_pk_add_f32 v[138:139], v[174:175], v[100:101] neg_lo:[0,1] neg_hi:[0,1]
	v_pk_fma_f32 v[100:101], v[0:1], v[98:99], v[108:109] op_sel_hi:[0,1,1] neg_lo:[0,0,1] neg_hi:[0,0,1]
	v_pk_add_f32 v[98:99], v[98:99], v[104:105]
	v_lshlrev_b32_e32 v188, 16, v170
	v_and_b32_e32 v189, 0xffff0000, v170
	v_fma_f32 v217, -v177, v182, v180
	v_pk_add_f32 v[2:3], v[2:3], v[192:193]
	v_cvt_pk_bf16_f32 v27, v100, v101
	v_pk_fma_f32 v[100:101], v[112:113], v[98:99], v[114:115] op_sel_hi:[0,1,1] neg_lo:[0,0,1] neg_hi:[0,0,1]
	v_pk_add_f32 v[98:99], v[98:99], v[136:137]
	v_lshlrev_b32_e32 v210, 16, v173
	v_lshlrev_b32_e32 v190, 16, v172
	v_and_b32_e32 v191, 0xffff0000, v172
	v_fmac_f32_e32 v182, v217, v178
	v_cvt_pk_bf16_f32 v26, v18, v19
	v_cvt_pk_bf16_f32 v18, v14, v15
	v_pk_fma_f32 v[14:15], v[150:151], v[2:3], v[140:141] op_sel_hi:[0,1,1] neg_lo:[0,0,1] neg_hi:[0,0,1]
	v_pk_add_f32 v[140:141], v[188:189], v[102:103] neg_lo:[0,1] neg_hi:[0,1]
	v_cvt_pk_bf16_f32 v23, v100, v101
	v_pk_fma_f32 v[100:101], v[128:129], v[98:99], v[116:117] op_sel_hi:[0,1,1] neg_lo:[0,0,1] neg_hi:[0,0,1]
	v_pk_add_f32 v[98:99], v[98:99], v[138:139]
	v_lshlrev_b32_e32 v212, 16, v186
	v_and_b32_e32 v213, 0xffff0000, v186
	v_fma_f32 v177, -v177, v182, v180
	v_pk_add_f32 v[132:133], v[2:3], v[208:209]
	v_pk_add_f32 v[6:7], v[210:211], v[6:7] neg_lo:[0,1] neg_hi:[0,1]
	v_cvt_pk_bf16_f32 v19, v100, v101
	v_pk_fma_f32 v[100:101], v[150:151], v[98:99], v[118:119] op_sel_hi:[0,1,1] neg_lo:[0,0,1] neg_hi:[0,0,1]
	v_pk_add_f32 v[98:99], v[98:99], v[140:141]
	v_pk_add_f32 v[44:45], v[190:191], v[44:45] neg_lo:[0,1] neg_hi:[0,1]
	v_div_fmas_f32 v177, v177, v178, v182
	v_pk_fma_f32 v[2:3], v[158:159], v[132:133], v[144:145] op_sel_hi:[0,1,1] neg_lo:[0,0,1] neg_hi:[0,0,1]
	v_pk_add_f32 v[132:133], v[132:133], v[6:7]
	v_pk_add_f32 v[10:11], v[212:213], v[10:11] neg_lo:[0,1] neg_hi:[0,1]
	v_pk_add_f32 v[44:45], v[98:99], v[44:45]
	v_pk_add_f32 v[94:95], v[214:215], v[94:95] neg_lo:[0,1] neg_hi:[0,1]
	v_div_fixup_f32 v178, v177, v176, 1.0
	v_cvt_pk_bf16_f32 v14, v14, v15
	v_pk_fma_f32 v[6:7], v[166:167], v[132:133], v[146:147] op_sel_hi:[0,1,1] neg_lo:[0,0,1] neg_hi:[0,0,1]
	v_pk_add_f32 v[132:133], v[132:133], v[10:11]
	v_pk_add_f32 v[42:43], v[222:223], v[42:43] neg_lo:[0,1] neg_hi:[0,1]
	v_cvt_pk_bf16_f32 v15, v100, v101
	v_pk_fma_f32 v[100:101], v[158:159], v[98:99], v[120:121] op_sel_hi:[0,1,1] neg_lo:[0,0,1] neg_hi:[0,0,1]
	v_pk_fma_f32 v[98:99], v[166:167], v[44:45], v[122:123] op_sel_hi:[0,1,1] neg_lo:[0,0,1] neg_hi:[0,0,1]
	v_pk_add_f32 v[44:45], v[44:45], v[94:95]
	v_pk_fma_f32 v[10:11], v[178:179], v[132:133], v[148:149] op_sel_hi:[0,1,1] neg_lo:[0,0,1] neg_hi:[0,0,1]
	v_pk_add_f32 v[42:43], v[132:133], v[42:43]
	v_lshlrev_b32_e32 v132, 16, v199
	v_and_b32_e32 v133, 0xffff0000, v199
	v_pk_fma_f32 v[94:95], v[178:179], v[44:45], v[124:125] op_sel_hi:[0,1,1] neg_lo:[0,0,1] neg_hi:[0,0,1]
	v_lshlrev_b32_e32 v152, 16, v126
	v_and_b32_e32 v153, 0xffff0000, v126
	v_cvt_pk_bf16_f32 v10, v10, v11
	v_cvt_pk_bf16_f32 v11, v94, v95
	v_pk_add_f32 v[94:95], v[132:133], v[96:97] neg_lo:[0,1] neg_hi:[0,1]
	v_pk_add_f32 v[96:97], v[28:29], 0 op_sel_hi:[1,0]
	v_cvt_pk_bf16_f32 v6, v6, v7
	v_cvt_pk_bf16_f32 v7, v98, v99
	v_pk_add_f32 v[98:99], v[152:153], v[16:17] neg_lo:[0,1] neg_hi:[0,1]
	v_pk_add_f32 v[16:17], v[96:97], v[16:17]
	v_lshlrev_b32_e32 v4, 16, v5
	v_pk_add_f32 v[16:17], v[16:17], v[20:21]
	v_and_b32_e32 v5, 0xffff0000, v5
	v_pk_add_f32 v[16:17], v[16:17], v[24:25]
	v_pk_add_f32 v[4:5], v[4:5], v[28:29] neg_lo:[0,1] neg_hi:[0,1]
	v_pk_add_f32 v[16:17], v[16:17], v[8:9]
	v_lshlrev_b32_e32 v162, 16, v142
	v_pk_add_f32 v[16:17], v[16:17], v[12:13]
	v_lshlrev_b32_e32 v170, 16, v156
	v_pk_add_f32 v[16:17], v[16:17], v[76:77]
	v_cvt_pk_bf16_f32 v2, v2, v3
	v_pk_add_f32 v[16:17], v[16:17], v[80:81]
	v_cvt_pk_bf16_f32 v3, v100, v101
	v_pk_add_f32 v[16:17], v[16:17], v[78:79]
	v_pk_add_f32 v[100:101], v[162:163], v[20:21] neg_lo:[0,1] neg_hi:[0,1]
	v_pk_add_f32 v[16:17], v[16:17], v[82:83]
	v_lshlrev_b32_e32 v172, 16, v160
	v_pk_add_f32 v[16:17], v[16:17], v[84:85]
	v_and_b32_e32 v173, 0xffff0000, v160
	v_pk_add_f32 v[16:17], v[16:17], v[86:87]
	v_pk_add_f32 v[102:103], v[170:171], v[24:25] neg_lo:[0,1] neg_hi:[0,1]
	v_pk_add_f32 v[16:17], v[16:17], v[88:89]
	v_lshlrev_b32_e32 v186, 16, v168
	v_pk_add_f32 v[16:17], v[16:17], v[90:91]
	v_and_b32_e32 v187, 0xffff0000, v168
	v_pk_add_f32 v[16:17], v[16:17], v[92:93]
	v_pk_add_f32 v[8:9], v[172:173], v[8:9] neg_lo:[0,1] neg_hi:[0,1]
	v_pk_add_f32 v[16:17], v[16:17], v[40:41]
	v_pk_add_f32 v[44:45], v[44:45], v[94:95]
	v_pk_add_f32 v[4:5], v[16:17], v[4:5]
	v_pk_fma_f32 v[20:21], v[0:1], v[16:17], v[78:79] op_sel_hi:[0,1,1] neg_lo:[0,0,1] neg_hi:[0,0,1]
	v_pk_fma_f32 v[16:17], v[112:113], v[4:5], v[82:83] op_sel_hi:[0,1,1] neg_lo:[0,0,1] neg_hi:[0,0,1]
	v_pk_add_f32 v[4:5], v[4:5], v[98:99]
	v_cvt_pk_bf16_f32 v24, v16, v17
	v_pk_fma_f32 v[16:17], v[128:129], v[4:5], v[84:85] op_sel_hi:[0,1,1] neg_lo:[0,0,1] neg_hi:[0,0,1]
	v_pk_add_f32 v[4:5], v[4:5], v[100:101]
	v_lshlrev_b32_e32 v94, 16, v198
	v_pk_add_f32 v[78:79], v[4:5], v[102:103]
	v_and_b32_e32 v95, 0xffff0000, v198
	v_cvt_pk_bf16_f32 v28, v20, v21
	v_cvt_pk_bf16_f32 v20, v16, v17
	v_pk_fma_f32 v[16:17], v[150:151], v[4:5], v[86:87] op_sel_hi:[0,1,1] neg_lo:[0,0,1] neg_hi:[0,0,1]
	v_pk_fma_f32 v[4:5], v[158:159], v[78:79], v[88:89] op_sel_hi:[0,1,1] neg_lo:[0,0,1] neg_hi:[0,0,1]
	v_pk_add_f32 v[78:79], v[78:79], v[8:9]
	v_pk_add_f32 v[12:13], v[186:187], v[12:13] neg_lo:[0,1] neg_hi:[0,1]
	v_pk_fma_f32 v[8:9], v[166:167], v[78:79], v[90:91] op_sel_hi:[0,1,1] neg_lo:[0,0,1] neg_hi:[0,0,1]
	v_pk_add_f32 v[78:79], v[78:79], v[12:13]
	v_pk_add_f32 v[76:77], v[94:95], v[76:77] neg_lo:[0,1] neg_hi:[0,1]
	v_lshlrev_b32_e32 v126, 16, v127
	v_and_b32_e32 v127, 0xffff0000, v127
	v_pk_fma_f32 v[12:13], v[178:179], v[78:79], v[92:93] op_sel_hi:[0,1,1] neg_lo:[0,0,1] neg_hi:[0,0,1]
	v_pk_add_f32 v[76:77], v[78:79], v[76:77]
	v_pk_add_f32 v[78:79], v[58:59], 0 op_sel_hi:[1,0]
	v_pk_add_f32 v[80:81], v[126:127], v[52:53] neg_lo:[0,1] neg_hi:[0,1]
	v_pk_add_f32 v[52:53], v[78:79], v[52:53]
	v_lshlrev_b32_e32 v106, 16, v107
	v_pk_add_f32 v[52:53], v[52:53], v[54:55]
	v_and_b32_e32 v107, 0xffff0000, v107
	v_pk_add_f32 v[52:53], v[52:53], v[56:57]
	v_lshlrev_b32_e32 v142, 16, v143
	v_pk_add_f32 v[52:53], v[52:53], v[46:47]
	v_and_b32_e32 v143, 0xffff0000, v143
	v_pk_add_f32 v[52:53], v[52:53], v[48:49]
	v_pk_add_f32 v[58:59], v[106:107], v[58:59] neg_lo:[0,1] neg_hi:[0,1]
	v_pk_add_f32 v[52:53], v[52:53], v[50:51]
	v_pk_add_f32 v[82:83], v[142:143], v[54:55] neg_lo:[0,1] neg_hi:[0,1]
	v_pk_add_f32 v[52:53], v[52:53], v[62:63]
	v_lshlrev_b32_e32 v156, 16, v157
	v_pk_add_f32 v[52:53], v[52:53], v[60:61]
	v_and_b32_e32 v157, 0xffff0000, v157
	v_pk_add_f32 v[52:53], v[52:53], v[64:65]
	v_lshlrev_b32_e32 v160, 16, v161
	v_pk_add_f32 v[52:53], v[52:53], v[66:67]
	v_and_b32_e32 v161, 0xffff0000, v161
	v_pk_add_f32 v[52:53], v[52:53], v[68:69]
	v_pk_add_f32 v[84:85], v[156:157], v[56:57] neg_lo:[0,1] neg_hi:[0,1]
	v_pk_add_f32 v[52:53], v[52:53], v[70:71]
	v_lshlrev_b32_e32 v168, 16, v169
	v_pk_add_f32 v[52:53], v[52:53], v[72:73]
	v_and_b32_e32 v169, 0xffff0000, v169
	v_pk_add_f32 v[52:53], v[52:53], v[74:75]
	v_pk_add_f32 v[46:47], v[160:161], v[46:47] neg_lo:[0,1] neg_hi:[0,1]
	v_pk_add_f32 v[52:53], v[52:53], v[36:37]
	v_pk_add_f32 v[48:49], v[168:169], v[48:49] neg_lo:[0,1] neg_hi:[0,1]
	v_pk_fma_f32 v[54:55], v[0:1], v[52:53], v[60:61] op_sel_hi:[0,1,1] neg_lo:[0,0,1] neg_hi:[0,0,1]
	v_pk_add_f32 v[52:53], v[52:53], v[58:59]
	v_cvt_pk_bf16_f32 v29, v54, v55
	v_pk_fma_f32 v[54:55], v[112:113], v[52:53], v[64:65] op_sel_hi:[0,1,1] neg_lo:[0,0,1] neg_hi:[0,0,1]
	v_pk_add_f32 v[52:53], v[52:53], v[80:81]
	v_cvt_pk_bf16_f32 v25, v54, v55
	v_pk_fma_f32 v[54:55], v[128:129], v[52:53], v[66:67] op_sel_hi:[0,1,1] neg_lo:[0,0,1] neg_hi:[0,0,1]
	v_pk_add_f32 v[52:53], v[52:53], v[82:83]
	v_cvt_pk_bf16_f32 v21, v54, v55
	v_pk_fma_f32 v[54:55], v[150:151], v[52:53], v[68:69] op_sel_hi:[0,1,1] neg_lo:[0,0,1] neg_hi:[0,0,1]
	v_pk_add_f32 v[52:53], v[52:53], v[84:85]
	v_cvt_pk_bf16_f32 v16, v16, v17
	v_pk_add_f32 v[46:47], v[52:53], v[46:47]
	v_cvt_pk_bf16_f32 v17, v54, v55
	v_pk_fma_f32 v[54:55], v[158:159], v[52:53], v[70:71] op_sel_hi:[0,1,1] neg_lo:[0,0,1] neg_hi:[0,0,1]
	v_pk_fma_f32 v[52:53], v[166:167], v[46:47], v[72:73] op_sel_hi:[0,1,1] neg_lo:[0,0,1] neg_hi:[0,0,1]
	v_pk_add_f32 v[46:47], v[46:47], v[48:49]
	v_and_b32_e32 v177, 0xffff0000, v197
	v_lshlrev_b32_e32 v176, 16, v197
	v_pk_fma_f32 v[48:49], v[178:179], v[46:47], v[74:75] op_sel_hi:[0,1,1] neg_lo:[0,0,1] neg_hi:[0,0,1]
	global_store_dwordx4 v[30:31], v[26:29], off
	global_store_dwordx4 v[30:31], v[22:25], off offset:1024
	global_store_dwordx4 v[30:31], v[18:21], off offset:2048
	global_store_dwordx4 v[30:31], v[14:17], off offset:3072
	v_cvt_pk_bf16_f32 v4, v4, v5
	v_cvt_pk_bf16_f32 v12, v12, v13
	v_add_co_u32_e32 v14, vcc, s87, v30
	v_cvt_pk_bf16_f32 v5, v54, v55
	v_cvt_pk_bf16_f32 v13, v48, v49
	v_pk_add_f32 v[48:49], v[176:177], v[50:51] neg_lo:[0,1] neg_hi:[0,1]
	v_addc_co_u32_e32 v15, vcc, 0, v31, vcc
	v_cvt_pk_bf16_f32 v8, v8, v9
	v_cvt_pk_bf16_f32 v9, v52, v53
	global_store_dwordx4 v[14:15], v[2:5], off
	global_store_dwordx4 v[14:15], v[6:9], off offset:1024
	global_store_dwordx4 v[14:15], v[10:13], off offset:2048
	v_pk_add_f32 v[2:3], v[46:47], v[48:49]
	v_max_i32_e32 v0, 8, v196
	v_mov_b32_e32 v5, 15
	v_mov_b32_e32 v4, 8
.LBB0_503:
	s_or_b64 exec, exec, s[80:81]
	s_and_saveexec_b64 s[80:81], s[74:75]
	s_cbranch_execz .LBB0_505
	v_add_u32_e32 v0, -2, v183
	v_min_u32_e32 v0, v0, v179
	v_mad_u64_u32 v[2:3], s[0:1], v0, s72, v[32:33]
	v_add_u32_e32 v250, -2, v167
	v_max_i32_e32 v250, 0, v250
	v_min_u32_e32 v250, v250, v179
	v_mad_u64_u32 v[250:251], s[98:99], v250, s72, v[32:33]
	global_load_dwordx4 v[226:229], v[250:251], off
	v_add_u32_e32 v250, -1, v167
	v_max_i32_e32 v250, 0, v250
	v_min_u32_e32 v250, v250, v179
	v_mad_u64_u32 v[250:251], s[98:99], v250, s72, v[32:33]
	global_load_dwordx4 v[230:233], v[250:251], off
	v_add_u32_e32 v250, 0, v167
	v_max_i32_e32 v250, 0, v250
	v_min_u32_e32 v250, v250, v179
	v_mad_u64_u32 v[250:251], s[98:99], v250, s72, v[32:33]
	global_load_dwordx4 v[234:237], v[250:251], off
	v_add_u32_e32 v250, 1, v167
	v_max_i32_e32 v250, 0, v250
	v_min_u32_e32 v250, v250, v179
	v_mad_u64_u32 v[250:251], s[98:99], v250, s72, v[32:33]
	global_load_dwordx4 v[238:241], v[250:251], off
	v_add_u32_e32 v250, 2, v167
	v_max_i32_e32 v250, 0, v250
	v_min_u32_e32 v250, v250, v179
	v_mad_u64_u32 v[250:251], s[98:99], v250, s72, v[32:33]
	global_load_dwordx4 v[242:245], v[250:251], off
	v_add_u32_e32 v250, 3, v167
	v_max_i32_e32 v250, 0, v250
	v_min_u32_e32 v250, v250, v179
	v_mad_u64_u32 v[250:251], s[98:99], v250, s72, v[32:33]
	global_load_dwordx4 v[246:249], v[250:251], off
	v_cmp_lt_i32_e32 vcc, 1, v167
	s_and_b64 vcc, vcc, s[4:5]
	v_or_b32_e32 v40, 2, v167
	v_or_b32_e32 v36, 3, v167
	v_or_b32_e32 v35, 4, v167
	v_or_b32_e32 v34, 5, v167
	v_or_b32_e32 v59, 6, v167
	v_or_b32_e32 v47, 7, v167
	s_waitcnt vmcnt(5)
	v_cndmask_b32_e32 v8, 0, v226, vcc
	v_min_u32_e32 v2, v195, v179
	v_cndmask_b32_e32 v7, 0, v227, vcc
	v_mad_u64_u32 v[2:3], s[0:1], v2, s72, v[32:33]
	v_cndmask_b32_e32 v6, 0, v228, vcc
	v_cndmask_b32_e32 v0, 0, v229, vcc
	v_add_u32_e32 v250, 4, v167
	v_max_i32_e32 v250, 0, v250
	v_min_u32_e32 v250, v250, v179
	v_mad_u64_u32 v[250:251], s[98:99], v250, s72, v[32:33]
	global_load_dwordx4 v[226:229], v[250:251], off
	v_cmp_lt_i32_e32 vcc, 0, v167
	s_and_b64 vcc, vcc, s[4:5]
	v_cmp_lt_i32_e64 s[0:1], v167, v131
	v_lshlrev_b32_e32 v42, 16, v8
	v_and_b32_e32 v43, 0xffff0000, v8
	v_lshlrev_b32_e32 v20, 16, v7
	v_and_b32_e32 v21, 0xffff0000, v7
	v_lshlrev_b32_e32 v10, 16, v6
	v_and_b32_e32 v11, 0xffff0000, v6
	s_waitcnt vmcnt(5)
	v_cndmask_b32_e32 v14, 0, v230, vcc
	v_max_i32_e32 v2, 0, v167
	v_cndmask_b32_e32 v12, 0, v231, vcc
	v_cndmask_b32_e32 v13, 0, v232, vcc
	v_cndmask_b32_e32 v9, 0, v233, vcc
	v_add_u32_e32 v250, 5, v167
	v_max_i32_e32 v250, 0, v250
	v_min_u32_e32 v250, v250, v179
	v_mad_u64_u32 v[250:251], s[98:99], v250, s72, v[32:33]
	global_load_dwordx4 v[230:233], v[250:251], off
	v_cmp_lt_i32_e32 vcc, -1, v181
	v_min_u32_e32 v2, v2, v179
	s_and_b64 vcc, vcc, s[0:1]
	v_mad_u64_u32 v[2:3], s[0:1], v2, s72, v[32:33]
	v_cmp_lt_i32_e64 s[0:1], v129, v131
	v_lshlrev_b32_e32 v44, 16, v14
	v_and_b32_e32 v45, 0xffff0000, v14
	v_lshlrev_b32_e32 v22, 16, v12
	v_and_b32_e32 v23, 0xffff0000, v12
	v_lshlrev_b32_e32 v12, 16, v13
	v_and_b32_e32 v13, 0xffff0000, v13
	s_waitcnt vmcnt(5)
	v_cndmask_b32_e32 v18, 0, v234, vcc
	v_cndmask_b32_e32 v17, 0, v235, vcc
	v_cndmask_b32_e32 v15, 0, v236, vcc
	v_cndmask_b32_e32 v16, 0, v237, vcc
	v_add_u32_e32 v250, 6, v167
	v_max_i32_e32 v250, 0, v250
	v_min_u32_e32 v250, v250, v179
	v_mad_u64_u32 v[250:251], s[98:99], v250, s72, v[32:33]
	global_load_dwordx4 v[234:237], v[250:251], off
	v_cmp_lt_i32_e32 vcc, -2, v167
	v_min_u32_e32 v2, v194, v179
	s_and_b64 vcc, vcc, s[0:1]
	v_mad_u64_u32 v[2:3], s[0:1], v2, s72, v[32:33]
	v_cmp_lt_i32_e64 s[0:1], v40, v131
	v_lshlrev_b32_e32 v48, 16, v18
	v_and_b32_e32 v49, 0xffff0000, v18
	v_lshlrev_b32_e32 v24, 16, v17
	v_and_b32_e32 v25, 0xffff0000, v17
	v_lshlrev_b32_e32 v6, 16, v16
	v_and_b32_e32 v7, 0xffff0000, v16
	v_lshlrev_b32_e32 v14, 16, v15
	v_and_b32_e32 v15, 0xffff0000, v15
	s_waitcnt vmcnt(5)
	v_cndmask_b32_e32 v26, 0, v238, vcc
	v_max_i32_e32 v2, 0, v40
	v_cndmask_b32_e32 v27, 0, v239, vcc
	v_cndmask_b32_e32 v53, 0, v240, vcc
	v_cndmask_b32_e32 v52, 0, v241, vcc
	v_add_u32_e32 v250, 7, v167
	v_max_i32_e32 v250, 0, v250
	v_min_u32_e32 v250, v250, v179
	v_mad_u64_u32 v[250:251], s[98:99], v250, s72, v[32:33]
	global_load_dwordx4 v[238:241], v[250:251], off
	v_cmp_lt_i32_e32 vcc, -3, v167
	v_min_u32_e32 v2, v2, v179
	s_and_b64 vcc, vcc, s[0:1]
	v_mad_u64_u32 v[2:3], s[0:1], v2, s72, v[32:33]
	v_cmp_lt_i32_e64 s[0:1], v36, v131
	v_lshlrev_b32_e32 v8, 16, v52
	v_lshlrev_b32_e32 v16, 16, v53
	v_and_b32_e32 v17, 0xffff0000, v53
	v_lshlrev_b32_e32 v50, 16, v26
	v_and_b32_e32 v51, 0xffff0000, v26
	v_lshlrev_b32_e32 v26, 16, v27
	v_and_b32_e32 v27, 0xffff0000, v27
	s_waitcnt vmcnt(5)
	v_cndmask_b32_e32 v46, 0, v242, vcc
	v_max_i32_e32 v2, 0, v36
	v_cndmask_b32_e32 v28, 0, v243, vcc
	v_cndmask_b32_e32 v29, 0, v244, vcc
	v_cndmask_b32_e32 v19, 0, v245, vcc
	v_add_u32_e32 v250, 8, v167
	v_max_i32_e32 v250, 0, v250
	v_min_u32_e32 v250, v250, v179
	v_mad_u64_u32 v[250:251], s[98:99], v250, s72, v[32:33]
	global_load_dwordx4 v[242:245], v[250:251], off
	v_cmp_lt_i32_e32 vcc, -4, v167
	v_min_u32_e32 v2, v2, v179
	s_and_b64 vcc, vcc, s[0:1]
	v_mad_u64_u32 v[2:3], s[0:1], v2, s72, v[32:33]
	v_cmp_lt_i32_e64 s[0:1], v35, v131
	v_lshlrev_b32_e32 v60, 16, v46
	v_and_b32_e32 v61, 0xffff0000, v46
	s_waitcnt vmcnt(5)
	v_cndmask_b32_e32 v62, 0, v246, vcc
	v_max_i32_e32 v2, 0, v35
	v_cndmask_b32_e32 v54, 0, v247, vcc
	v_cndmask_b32_e32 v55, 0, v248, vcc
	v_cndmask_b32_e32 v58, 0, v249, vcc
	v_cmp_lt_i32_e32 vcc, -5, v167
	v_min_u32_e32 v2, v2, v179
	s_and_b64 vcc, vcc, s[0:1]
	v_mad_u64_u32 v[2:3], s[0:1], v2, s72, v[32:33]
	v_cmp_lt_i32_e64 s[0:1], v34, v131
	v_and_b32_e32 v71, 0xffff0000, v62
	s_waitcnt vmcnt(4)
	v_cndmask_b32_e32 v65, 0, v226, vcc
	v_max_i32_e32 v2, 0, v34
	v_cndmask_b32_e32 v64, 0, v227, vcc
	v_cndmask_b32_e32 v56, 0, v228, vcc
	v_cndmask_b32_e32 v57, 0, v229, vcc
	v_cmp_lt_i32_e32 vcc, -6, v167
	v_min_u32_e32 v2, v2, v179
	s_and_b64 vcc, vcc, s[0:1]
	v_mad_u64_u32 v[2:3], s[0:1], v2, s72, v[32:33]
	v_cmp_lt_i32_e64 s[0:1], v59, v131
	v_and_b32_e32 v77, 0xffff0000, v65
	s_waitcnt vmcnt(3)
	v_cndmask_b32_e32 v75, 0, v230, vcc
	v_max_i32_e32 v2, 0, v59
	v_cndmask_b32_e32 v74, 0, v231, vcc
	v_cndmask_b32_e32 v66, 0, v232, vcc
	v_cndmask_b32_e32 v67, 0, v233, vcc
	v_cmp_lt_i32_e32 vcc, -7, v167
	v_min_u32_e32 v2, v2, v179
	s_and_b64 vcc, vcc, s[0:1]
	v_mad_u64_u32 v[2:3], s[0:1], v2, s72, v[32:33]
	v_cmp_lt_i32_e64 s[0:1], v47, v131
	v_lshlrev_b32_e32 v92, 16, v75
	v_and_b32_e32 v93, 0xffff0000, v75
	v_and_b32_e32 v75, 0xffff0000, v66
	s_waitcnt vmcnt(2)
	v_cndmask_b32_e32 v81, 0, v234, vcc
	v_max_i32_e32 v2, 0, v47
	v_cndmask_b32_e32 v79, 0, v235, vcc
	v_cndmask_b32_e32 v78, 0, v236, vcc
	v_cndmask_b32_e32 v69, 0, v237, vcc
	v_cmp_lt_i32_e32 vcc, -8, v167
	v_min_u32_e32 v2, v2, v179
	s_and_b64 vcc, vcc, s[0:1]
	v_mad_u64_u32 v[2:3], s[0:1], v2, s72, v[32:33]
	v_cmp_lt_i32_e64 s[0:1], v113, v131
	v_lshlrev_b32_e32 v100, 16, v79
	v_and_b32_e32 v101, 0xffff0000, v79
	v_and_b32_e32 v79, 0xffff0000, v69
	v_lshlrev_b32_e32 v96, 16, v81
	v_and_b32_e32 v97, 0xffff0000, v81
	s_waitcnt vmcnt(1)
	v_cndmask_b32_e32 v38, 0, v238, vcc
	v_max_i32_e32 v2, 0, v113
	v_cndmask_b32_e32 v39, 0, v239, vcc
	v_cndmask_b32_e32 v41, 0, v240, vcc
	v_cndmask_b32_e32 v37, 0, v241, vcc
	v_cmp_lt_i32_e32 vcc, -9, v167
	v_min_u32_e32 v2, v2, v179
	s_and_b64 vcc, vcc, s[0:1]
	v_mad_u64_u32 v[2:3], s[0:1], v2, s72, v[32:33]
	s_waitcnt vmcnt(0)
	v_cndmask_b32_e32 v90, 0, v242, vcc
	v_cndmask_b32_e32 v89, 0, v243, vcc
	v_lshlrev_b32_e32 v2, 16, v0
	v_and_b32_e32 v3, 0xffff0000, v0
	v_min_i32_e32 v0, v40, v131
	v_sub_u32_e32 v0, v0, v183
	v_add_u32_e32 v0, 2, v0
	v_cvt_f32_i32_e32 v0, v0
	v_cndmask_b32_e32 v88, 0, v244, vcc
	v_cndmask_b32_e32 v87, 0, v245, vcc
	v_lshlrev_b32_e32 v4, 16, v9
	v_div_scale_f32 v18, s[0:1], v0, v0, 1.0
	v_rcp_f32_e32 v32, v18
	v_and_b32_e32 v5, 0xffff0000, v9
	v_and_b32_e32 v9, 0xffff0000, v52
	v_max_i32_e32 v40, 2, v40
	v_fma_f32 v33, -v18, v32, 1.0
	v_fmac_f32_e32 v32, v33, v32
	v_div_scale_f32 v33, vcc, 1.0, v0, 1.0
	v_mul_f32_e32 v52, v33, v32
	v_fma_f32 v53, -v18, v52, v33
	v_fmac_f32_e32 v52, v53, v32
	v_fma_f32 v18, -v18, v52, v33
	v_div_fmas_f32 v18, v18, v32, v52
	v_max_i32_e32 v32, 2, v129
	v_min_i32_e32 v33, v36, v131
	v_sub_u32_e32 v32, v33, v32
	v_add_u32_e32 v32, 2, v32
	v_cvt_f32_i32_e32 v32, v32
	v_max_i32_e32 v36, 2, v36
	v_lshlrev_b32_e32 v104, 16, v90
	v_and_b32_e32 v105, 0xffff0000, v90
	v_div_scale_f32 v33, s[0:1], v32, v32, 1.0
	v_rcp_f32_e32 v46, v33
	v_div_fixup_f32 v0, v18, v0, 1.0
	v_lshlrev_b32_e32 v52, 16, v28
	v_and_b32_e32 v53, 0xffff0000, v28
	v_fma_f32 v63, -v33, v46, 1.0
	v_fmac_f32_e32 v46, v63, v46
	v_div_scale_f32 v63, vcc, 1.0, v32, 1.0
	v_mul_f32_e32 v68, v63, v46
	v_fma_f32 v70, -v33, v68, v63
	v_fmac_f32_e32 v68, v70, v46
	v_fma_f32 v33, -v33, v68, v63
	v_div_fmas_f32 v33, v33, v46, v68
	v_div_fixup_f32 v46, v33, v32, 1.0
	v_lshlrev_b32_e32 v32, 16, v58
	v_and_b32_e32 v33, 0xffff0000, v58
	v_min_i32_e32 v58, v35, v131
	v_sub_u32_e32 v40, v58, v40
	v_add_u32_e32 v40, 2, v40
	v_cvt_f32_i32_e32 v40, v40
	v_max_i32_e32 v35, 2, v35
	v_lshlrev_b32_e32 v70, 16, v62
	v_lshlrev_b32_e32 v62, 16, v54
	v_div_scale_f32 v58, s[0:1], v40, v40, 1.0
	v_rcp_f32_e32 v68, v58
	v_and_b32_e32 v63, 0xffff0000, v54
	v_lshlrev_b32_e32 v28, 16, v29
	v_and_b32_e32 v29, 0xffff0000, v29
	v_fma_f32 v72, -v58, v68, 1.0
	v_fmac_f32_e32 v68, v72, v68
	v_div_scale_f32 v72, vcc, 1.0, v40, 1.0
	v_mul_f32_e32 v73, v72, v68
	v_fma_f32 v76, -v58, v73, v72
	v_fmac_f32_e32 v73, v76, v68
	v_fma_f32 v58, -v58, v73, v72
	v_div_fmas_f32 v58, v58, v68, v73
	v_div_fixup_f32 v58, v58, v40, 1.0
	v_min_i32_e32 v40, v34, v131
	v_sub_u32_e32 v36, v40, v36
	v_add_u32_e32 v36, 2, v36
	v_cvt_f32_i32_e32 v36, v36
	v_max_i32_e32 v34, 2, v34
	v_lshlrev_b32_e32 v76, 16, v65
	v_lshlrev_b32_e32 v72, 16, v64
	v_div_scale_f32 v40, s[0:1], v36, v36, 1.0
	v_rcp_f32_e32 v68, v40
	v_and_b32_e32 v73, 0xffff0000, v64
	v_lshlrev_b32_e32 v54, 16, v55
	v_and_b32_e32 v55, 0xffff0000, v55
	v_fma_f32 v80, -v40, v68, 1.0
	v_fmac_f32_e32 v68, v80, v68
	v_div_scale_f32 v80, vcc, 1.0, v36, 1.0
	v_mul_f32_e32 v82, v80, v68
	v_fma_f32 v83, -v40, v82, v80
	v_fmac_f32_e32 v82, v83, v68
	v_fma_f32 v40, -v40, v82, v80
	v_div_fmas_f32 v40, v40, v68, v82
	v_div_fixup_f32 v68, v40, v36, 1.0
	v_min_i32_e32 v36, v59, v131
	v_sub_u32_e32 v35, v36, v35
	v_add_u32_e32 v35, 2, v35
	v_cvt_f32_i32_e32 v35, v35
	v_max_i32_e32 v59, 2, v59
	v_lshlrev_b32_e32 v82, 16, v74
	v_and_b32_e32 v83, 0xffff0000, v74
	v_div_scale_f32 v36, s[0:1], v35, v35, 1.0
	v_rcp_f32_e32 v40, v36
	v_lshlrev_b32_e32 v64, 16, v56
	v_and_b32_e32 v65, 0xffff0000, v56
	v_lshlrev_b32_e32 v74, 16, v66
	v_fma_f32 v80, -v36, v40, 1.0
	v_fmac_f32_e32 v40, v80, v40
	v_div_scale_f32 v80, vcc, 1.0, v35, 1.0
	v_mul_f32_e32 v84, v80, v40
	v_fma_f32 v85, -v36, v84, v80
	v_fmac_f32_e32 v84, v85, v40
	v_fma_f32 v36, -v36, v84, v80
	v_div_fmas_f32 v36, v36, v40, v84
	v_div_fixup_f32 v80, v36, v35, 1.0
	v_min_i32_e32 v35, v47, v131
	v_sub_u32_e32 v34, v35, v34
	v_add_u32_e32 v34, 2, v34
	v_cvt_f32_i32_e32 v34, v34
	v_lshlrev_b32_e32 v84, 16, v78
	v_and_b32_e32 v85, 0xffff0000, v78
	v_lshlrev_b32_e32 v78, 16, v69
	v_div_scale_f32 v35, s[0:1], v34, v34, 1.0
	v_rcp_f32_e32 v36, v35
	v_lshlrev_b32_e32 v18, 16, v19
	v_and_b32_e32 v19, 0xffff0000, v19
	v_lshlrev_b32_e32 v56, 16, v57
	v_fma_f32 v40, -v35, v36, 1.0
	v_fmac_f32_e32 v36, v40, v36
	v_div_scale_f32 v40, vcc, 1.0, v34, 1.0
	v_mul_f32_e32 v69, v40, v36
	v_fma_f32 v81, -v35, v69, v40
	v_fmac_f32_e32 v69, v81, v36
	v_fma_f32 v35, -v35, v69, v40
	v_div_fmas_f32 v35, v35, v36, v69
	v_min_i32_e32 v69, v113, v131
	v_sub_u32_e32 v59, v69, v59
	v_add_u32_e32 v59, 2, v59
	v_cvt_f32_i32_e32 v59, v59
	v_div_fixup_f32 v86, v35, v34, 1.0
	v_lshlrev_b32_e32 v34, 16, v38
	v_and_b32_e32 v35, 0xffff0000, v38
	v_div_scale_f32 v69, s[0:1], v59, v59, 1.0
	v_rcp_f32_e32 v81, v69
	v_lshlrev_b32_e32 v38, 16, v39
	v_and_b32_e32 v39, 0xffff0000, v39
	v_lshlrev_b32_e32 v40, 16, v41
	v_fma_f32 v91, -v69, v81, 1.0
	v_fmac_f32_e32 v81, v91, v81
	v_div_scale_f32 v91, vcc, 1.0, v59, 1.0
	v_mul_f32_e32 v94, v91, v81
	v_fma_f32 v95, -v69, v94, v91
	v_fmac_f32_e32 v94, v95, v81
	v_fma_f32 v69, -v69, v94, v91
	v_pk_add_f32 v[90:91], v[42:43], 0 op_sel_hi:[1,0]
	v_div_fmas_f32 v69, v69, v81, v94
	v_pk_add_f32 v[90:91], v[90:91], v[44:45]
	v_pk_add_f32 v[42:43], v[60:61], v[42:43] neg_lo:[0,1] neg_hi:[0,1]
	v_pk_add_f32 v[90:91], v[90:91], v[48:49]
	v_pk_add_f32 v[44:45], v[70:71], v[44:45] neg_lo:[0,1] neg_hi:[0,1]
	v_pk_add_f32 v[94:95], v[90:91], v[50:51]
	v_div_fixup_f32 v106, v69, v59, 1.0
	v_pk_add_f32 v[42:43], v[94:95], v[42:43]
	v_pk_fma_f32 v[90:91], v[0:1], v[94:95], v[48:49] op_sel_hi:[0,1,1] neg_lo:[0,0,1] neg_hi:[0,0,1]
	v_pk_fma_f32 v[94:95], v[46:47], v[42:43], v[50:51] op_sel_hi:[0,1,1] neg_lo:[0,0,1] neg_hi:[0,0,1]
	v_pk_add_f32 v[42:43], v[42:43], v[44:45]
	v_cvt_pk_bf16_f32 v94, v94, v95
	v_pk_fma_f32 v[44:45], v[58:59], v[42:43], v[60:61] op_sel_hi:[0,1,1] neg_lo:[0,0,1] neg_hi:[0,0,1]
	v_cvt_pk_bf16_f32 v98, v44, v45
	v_pk_add_f32 v[44:45], v[76:77], v[48:49] neg_lo:[0,1] neg_hi:[0,1]
	v_and_b32_e32 v41, 0xffff0000, v41
	v_pk_add_f32 v[42:43], v[42:43], v[44:45]
	v_cvt_pk_bf16_f32 v90, v90, v91
	v_pk_fma_f32 v[44:45], v[68:69], v[42:43], v[70:71] op_sel_hi:[0,1,1] neg_lo:[0,0,1] neg_hi:[0,0,1]
	v_cvt_pk_bf16_f32 v48, v44, v45
	v_pk_add_f32 v[44:45], v[92:93], v[50:51] neg_lo:[0,1] neg_hi:[0,1]
	v_pk_add_f32 v[50:51], v[20:21], 0 op_sel_hi:[1,0]
	v_pk_add_f32 v[42:43], v[42:43], v[44:45]
	v_pk_add_f32 v[50:51], v[50:51], v[22:23]
	v_pk_fma_f32 v[44:45], v[80:81], v[42:43], v[76:77] op_sel_hi:[0,1,1] neg_lo:[0,0,1] neg_hi:[0,0,1]
	v_cvt_pk_bf16_f32 v102, v44, v45
	v_pk_add_f32 v[44:45], v[96:97], v[60:61] neg_lo:[0,1] neg_hi:[0,1]
	v_pk_add_f32 v[50:51], v[50:51], v[24:25]
	v_pk_add_f32 v[42:43], v[42:43], v[44:45]
	v_pk_add_f32 v[50:51], v[50:51], v[26:27]
	v_pk_fma_f32 v[44:45], v[86:87], v[42:43], v[92:93] op_sel_hi:[0,1,1] neg_lo:[0,0,1] neg_hi:[0,0,1]
	v_cvt_pk_bf16_f32 v60, v44, v45
	v_pk_add_f32 v[44:45], v[34:35], v[70:71] neg_lo:[0,1] neg_hi:[0,1]
	v_pk_add_f32 v[20:21], v[52:53], v[20:21] neg_lo:[0,1] neg_hi:[0,1]
	v_pk_add_f32 v[42:43], v[42:43], v[44:45]
	v_pk_add_f32 v[20:21], v[50:51], v[20:21]
	v_pk_fma_f32 v[44:45], v[106:107], v[42:43], v[96:97] op_sel_hi:[0,1,1] neg_lo:[0,0,1] neg_hi:[0,0,1]
	v_pk_add_f32 v[22:23], v[62:63], v[22:23] neg_lo:[0,1] neg_hi:[0,1]
	v_cvt_pk_bf16_f32 v70, v44, v45
	v_pk_add_f32 v[44:45], v[104:105], v[76:77] neg_lo:[0,1] neg_hi:[0,1]
	v_pk_fma_f32 v[76:77], v[0:1], v[50:51], v[24:25] op_sel_hi:[0,1,1] neg_lo:[0,0,1] neg_hi:[0,0,1]
	v_pk_fma_f32 v[50:51], v[46:47], v[20:21], v[26:27] op_sel_hi:[0,1,1] neg_lo:[0,0,1] neg_hi:[0,0,1]
	v_pk_add_f32 v[20:21], v[20:21], v[22:23]
	v_pk_add_f32 v[42:43], v[42:43], v[44:45]
	v_pk_fma_f32 v[22:23], v[58:59], v[20:21], v[52:53] op_sel_hi:[0,1,1] neg_lo:[0,0,1] neg_hi:[0,0,1]
	v_cvt_pk_bf16_f32 v99, v22, v23
	v_pk_add_f32 v[22:23], v[72:73], v[24:25] neg_lo:[0,1] neg_hi:[0,1]
	v_lshlrev_b32_e32 v44, 16, v89
	v_pk_add_f32 v[20:21], v[20:21], v[22:23]
	v_and_b32_e32 v45, 0xffff0000, v89
	v_pk_fma_f32 v[22:23], v[68:69], v[20:21], v[62:63] op_sel_hi:[0,1,1] neg_lo:[0,0,1] neg_hi:[0,0,1]
	v_cvt_pk_bf16_f32 v49, v22, v23
	v_pk_add_f32 v[22:23], v[82:83], v[26:27] neg_lo:[0,1] neg_hi:[0,1]
	v_cvt_pk_bf16_f32 v95, v50, v51
	v_pk_add_f32 v[20:21], v[20:21], v[22:23]
	v_cvt_pk_bf16_f32 v91, v76, v77
	v_pk_fma_f32 v[22:23], v[80:81], v[20:21], v[72:73] op_sel_hi:[0,1,1] neg_lo:[0,0,1] neg_hi:[0,0,1]
	v_cvt_pk_bf16_f32 v103, v22, v23
	v_pk_add_f32 v[22:23], v[100:101], v[52:53] neg_lo:[0,1] neg_hi:[0,1]
	v_and_b32_e32 v57, 0xffff0000, v57
	v_pk_add_f32 v[20:21], v[20:21], v[22:23]
	v_lshlrev_b32_e32 v66, 16, v67
	v_pk_fma_f32 v[22:23], v[86:87], v[20:21], v[82:83] op_sel_hi:[0,1,1] neg_lo:[0,0,1] neg_hi:[0,0,1]
	v_cvt_pk_bf16_f32 v61, v22, v23
	v_pk_add_f32 v[22:23], v[38:39], v[62:63] neg_lo:[0,1] neg_hi:[0,1]
	v_and_b32_e32 v67, 0xffff0000, v67
	v_pk_add_f32 v[20:21], v[20:21], v[22:23]
	v_lshlrev_b32_e32 v36, 16, v37
	v_pk_fma_f32 v[22:23], v[106:107], v[20:21], v[100:101] op_sel_hi:[0,1,1] neg_lo:[0,0,1] neg_hi:[0,0,1]
	v_cvt_pk_bf16_f32 v71, v22, v23
	v_pk_add_f32 v[22:23], v[44:45], v[72:73] neg_lo:[0,1] neg_hi:[0,1]
	v_and_b32_e32 v37, 0xffff0000, v37
	v_pk_add_f32 v[44:45], v[20:21], v[22:23]
	v_pk_add_f32 v[22:23], v[10:11], 0 op_sel_hi:[1,0]
	v_pk_add_f32 v[10:11], v[28:29], v[10:11] neg_lo:[0,1] neg_hi:[0,1]
	v_pk_add_f32 v[22:23], v[22:23], v[12:13]
	v_pk_add_f32 v[12:13], v[54:55], v[12:13] neg_lo:[0,1] neg_hi:[0,1]
	v_pk_add_f32 v[22:23], v[22:23], v[14:15]
	v_lshlrev_b32_e32 v20, 16, v88
	v_pk_add_f32 v[22:23], v[22:23], v[16:17]
	v_and_b32_e32 v21, 0xffff0000, v88
	v_pk_add_f32 v[10:11], v[22:23], v[10:11]
	v_pk_fma_f32 v[24:25], v[0:1], v[22:23], v[14:15] op_sel_hi:[0,1,1] neg_lo:[0,0,1] neg_hi:[0,0,1]
	v_pk_fma_f32 v[22:23], v[46:47], v[10:11], v[16:17] op_sel_hi:[0,1,1] neg_lo:[0,0,1] neg_hi:[0,0,1]
	v_pk_add_f32 v[10:11], v[10:11], v[12:13]
	v_and_b32_e32 v109, 0xffff0000, v87
	v_pk_fma_f32 v[12:13], v[58:59], v[10:11], v[28:29] op_sel_hi:[0,1,1] neg_lo:[0,0,1] neg_hi:[0,0,1]
	v_cvt_pk_bf16_f32 v100, v12, v13
	v_pk_add_f32 v[12:13], v[64:65], v[14:15] neg_lo:[0,1] neg_hi:[0,1]
	v_lshlrev_b32_e32 v108, 16, v87
	v_pk_add_f32 v[10:11], v[10:11], v[12:13]
	v_cvt_pk_bf16_f32 v92, v24, v25
	v_pk_fma_f32 v[12:13], v[68:69], v[10:11], v[54:55] op_sel_hi:[0,1,1] neg_lo:[0,0,1] neg_hi:[0,0,1]
	v_cvt_pk_bf16_f32 v50, v12, v13
	v_pk_add_f32 v[12:13], v[74:75], v[16:17] neg_lo:[0,1] neg_hi:[0,1]
	v_cvt_pk_bf16_f32 v96, v22, v23
	v_pk_add_f32 v[10:11], v[10:11], v[12:13]
	s_nop 0
	v_pk_fma_f32 v[12:13], v[80:81], v[10:11], v[64:65] op_sel_hi:[0,1,1] neg_lo:[0,0,1] neg_hi:[0,0,1]
	v_cvt_pk_bf16_f32 v104, v12, v13
	v_pk_add_f32 v[12:13], v[84:85], v[28:29] neg_lo:[0,1] neg_hi:[0,1]
	s_nop 0
	v_pk_add_f32 v[10:11], v[10:11], v[12:13]
	s_nop 0
	v_pk_fma_f32 v[12:13], v[86:87], v[10:11], v[74:75] op_sel_hi:[0,1,1] neg_lo:[0,0,1] neg_hi:[0,0,1]
	v_cvt_pk_bf16_f32 v62, v12, v13
	v_pk_add_f32 v[12:13], v[40:41], v[54:55] neg_lo:[0,1] neg_hi:[0,1]
	s_nop 0
	v_pk_add_f32 v[10:11], v[10:11], v[12:13]
	s_nop 0
	v_pk_fma_f32 v[12:13], v[106:107], v[10:11], v[84:85] op_sel_hi:[0,1,1] neg_lo:[0,0,1] neg_hi:[0,0,1]
	v_cvt_pk_bf16_f32 v72, v12, v13
	v_pk_add_f32 v[12:13], v[20:21], v[64:65] neg_lo:[0,1] neg_hi:[0,1]
	s_nop 0
	v_pk_add_f32 v[76:77], v[10:11], v[12:13]
	v_pk_add_f32 v[10:11], v[2:3], 0 op_sel_hi:[1,0]
	v_pk_add_f32 v[2:3], v[18:19], v[2:3] neg_lo:[0,1] neg_hi:[0,1]
	v_pk_add_f32 v[10:11], v[10:11], v[4:5]
	v_pk_add_f32 v[4:5], v[32:33], v[4:5] neg_lo:[0,1] neg_hi:[0,1]
	v_pk_add_f32 v[10:11], v[10:11], v[6:7]
	s_nop 0
	v_pk_add_f32 v[10:11], v[10:11], v[8:9]
	s_nop 0
	v_pk_add_f32 v[2:3], v[10:11], v[2:3]
	v_pk_fma_f32 v[12:13], v[0:1], v[10:11], v[6:7] op_sel_hi:[0,1,1] neg_lo:[0,0,1] neg_hi:[0,0,1]
	v_pk_fma_f32 v[10:11], v[46:47], v[2:3], v[8:9] op_sel_hi:[0,1,1] neg_lo:[0,0,1] neg_hi:[0,0,1]
	v_pk_add_f32 v[2:3], v[2:3], v[4:5]
	v_cvt_pk_bf16_f32 v93, v12, v13
	v_pk_fma_f32 v[4:5], v[58:59], v[2:3], v[18:19] op_sel_hi:[0,1,1] neg_lo:[0,0,1] neg_hi:[0,0,1]
	v_cvt_pk_bf16_f32 v101, v4, v5
	v_pk_add_f32 v[4:5], v[56:57], v[6:7] neg_lo:[0,1] neg_hi:[0,1]
	v_add_co_u32_e32 v6, vcc, s87, v30
	v_pk_add_f32 v[2:3], v[2:3], v[4:5]
	s_nop 0
	v_addc_co_u32_e32 v7, vcc, 0, v31, vcc
	v_pk_fma_f32 v[4:5], v[68:69], v[2:3], v[32:33] op_sel_hi:[0,1,1] neg_lo:[0,0,1] neg_hi:[0,0,1]
	v_cvt_pk_bf16_f32 v51, v4, v5
	v_pk_add_f32 v[4:5], v[66:67], v[8:9] neg_lo:[0,1] neg_hi:[0,1]
	v_max_i32_e32 v0, 2, v47
	v_pk_add_f32 v[2:3], v[2:3], v[4:5]
	v_cvt_pk_bf16_f32 v97, v10, v11
	v_pk_fma_f32 v[4:5], v[80:81], v[2:3], v[56:57] op_sel_hi:[0,1,1] neg_lo:[0,0,1] neg_hi:[0,0,1]
	v_cvt_pk_bf16_f32 v105, v4, v5
	v_pk_add_f32 v[4:5], v[78:79], v[18:19] neg_lo:[0,1] neg_hi:[0,1]
	global_store_dwordx4 v[30:31], v[90:93], off
	global_store_dwordx4 v[30:31], v[94:97], off offset:1024
	global_store_dwordx4 v[30:31], v[98:101], off offset:2048
	global_store_dwordx4 v[30:31], v[48:51], off offset:3072
	v_pk_add_f32 v[2:3], v[2:3], v[4:5]
	s_nop 0
	v_pk_fma_f32 v[4:5], v[86:87], v[2:3], v[66:67] op_sel_hi:[0,1,1] neg_lo:[0,0,1] neg_hi:[0,0,1]
	v_cvt_pk_bf16_f32 v63, v4, v5
	v_pk_add_f32 v[4:5], v[36:37], v[32:33] neg_lo:[0,1] neg_hi:[0,1]
	s_nop 0
	v_pk_add_f32 v[2:3], v[2:3], v[4:5]
	s_nop 0
	v_pk_fma_f32 v[4:5], v[106:107], v[2:3], v[78:79] op_sel_hi:[0,1,1] neg_lo:[0,0,1] neg_hi:[0,0,1]
	v_cvt_pk_bf16_f32 v73, v4, v5
	v_pk_add_f32 v[4:5], v[108:109], v[56:57] neg_lo:[0,1] neg_hi:[0,1]
	global_store_dwordx4 v[6:7], v[102:105], off
	global_store_dwordx4 v[6:7], v[60:63], off offset:1024
	global_store_dwordx4 v[6:7], v[70:73], off offset:2048
	v_pk_add_f32 v[2:3], v[2:3], v[4:5]
	v_mov_b32_e32 v5, 9
	v_mov_b32_e32 v4, 2

.LBB0_506:
	s_andn2_saveexec_b64 s[4:5], s[88:89]
	s_cbranch_execz .LBB0_508
	v_max_i32_e32 v0, 1, v167
	v_add_u32_e32 v2, -1, v0
	v_cmp_lt_i32_e32 vcc, 0, v167
	v_cmp_le_i32_e64 s[0:1], v167, v131
	v_min_u32_e32 v2, v2, v179
	s_and_b64 vcc, vcc, s[0:1]
	v_mad_u64_u32 v[2:3], s[0:1], v2, s72, v[32:33]
	v_add_u32_e32 v250, -1, v167
	v_max_i32_e32 v250, 0, v250
	v_min_u32_e32 v250, v250, v179
	v_mad_u64_u32 v[250:251], s[98:99], v250, s72, v[32:33]
	global_load_dwordx4 v[226:229], v[250:251], off
	v_add_u32_e32 v250, 0, v167
	v_max_i32_e32 v250, 0, v250
	v_min_u32_e32 v250, v250, v179
	v_mad_u64_u32 v[250:251], s[98:99], v250, s72, v[32:33]
	global_load_dwordx4 v[230:233], v[250:251], off
	v_add_u32_e32 v250, 1, v167
	v_max_i32_e32 v250, 0, v250
	v_min_u32_e32 v250, v250, v179
	v_mad_u64_u32 v[250:251], s[98:99], v250, s72, v[32:33]
	global_load_dwordx4 v[234:237], v[250:251], off
	v_add_u32_e32 v250, 2, v167
	v_max_i32_e32 v250, 0, v250
	v_min_u32_e32 v250, v250, v179
	v_mad_u64_u32 v[250:251], s[98:99], v250, s72, v[32:33]
	global_load_dwordx4 v[238:241], v[250:251], off
	v_add_u32_e32 v250, 3, v167
	v_max_i32_e32 v250, 0, v250
	v_min_u32_e32 v250, v250, v179
	v_mad_u64_u32 v[250:251], s[98:99], v250, s72, v[32:33]
	global_load_dwordx4 v[242:245], v[250:251], off
	v_add_u32_e32 v250, 4, v167
	v_max_i32_e32 v250, 0, v250
	v_min_u32_e32 v250, v250, v179
	v_mad_u64_u32 v[250:251], s[98:99], v250, s72, v[32:33]
	global_load_dwordx4 v[246:249], v[250:251], off
	v_cmp_lt_i32_e64 s[0:1], v167, v131
	v_or_b32_e32 v18, 1, v167
	v_or_b32_e32 v44, 2, v167
	v_max_i32_e32 v10, 0, v44
	v_min_u32_e32 v10, v10, v179
	v_or_b32_e32 v50, 3, v167
	v_or_b32_e32 v56, 4, v167
	v_or_b32_e32 v35, 5, v167
	v_or_b32_e32 v34, 6, v167
	v_or_b32_e32 v21, 7, v167
	s_waitcnt vmcnt(5)
	v_cndmask_b32_e32 v9, 0, v226, vcc
	v_max_i32_e32 v2, 0, v167
	v_cndmask_b32_e32 v8, 0, v227, vcc
	v_cndmask_b32_e32 v6, 0, v228, vcc
	v_cndmask_b32_e32 v7, 0, v229, vcc
	v_add_u32_e32 v250, 5, v167
	v_max_i32_e32 v250, 0, v250
	v_min_u32_e32 v250, v250, v179
	v_mad_u64_u32 v[250:251], s[98:99], v250, s72, v[32:33]
	global_load_dwordx4 v[226:229], v[250:251], off
	v_cmp_lt_i32_e32 vcc, -1, v181
	v_min_u32_e32 v2, v2, v179
	s_and_b64 vcc, vcc, s[0:1]
	v_mad_u64_u32 v[2:3], s[0:1], v2, s72, v[32:33]
	v_lshlrev_b32_e32 v22, 16, v9
	v_and_b32_e32 v23, 0xffff0000, v9
	v_lshlrev_b32_e32 v14, 16, v8
	v_and_b32_e32 v15, 0xffff0000, v8
	s_waitcnt vmcnt(5)
	v_cndmask_b32_e32 v16, 0, v230, vcc
	v_max_i32_e32 v2, 0, v18
	v_min_u32_e32 v2, v2, v179
	v_cndmask_b32_e32 v17, 0, v231, vcc
	v_mad_u64_u32 v[2:3], s[0:1], v2, s72, v[32:33]
	v_cndmask_b32_e32 v26, 0, v232, vcc
	v_cndmask_b32_e32 v20, 0, v233, vcc
	v_add_u32_e32 v250, 6, v167
	v_max_i32_e32 v250, 0, v250
	v_min_u32_e32 v250, v250, v179
	v_mad_u64_u32 v[250:251], s[98:99], v250, s72, v[32:33]
	global_load_dwordx4 v[230:233], v[250:251], off
	v_cmp_lt_i32_e32 vcc, -3, v167
	v_cmp_lt_i32_e64 s[0:1], v44, v131
	s_and_b64 vcc, vcc, s[0:1]
	v_mad_u64_u32 v[10:11], s[0:1], v10, s72, v[32:33]
	v_cmp_lt_i32_e64 s[0:1], v50, v131
	v_lshlrev_b32_e32 v8, 16, v20
	v_and_b32_e32 v9, 0xffff0000, v20
	v_min_i32_e32 v20, v18, v131
	v_sub_u32_e32 v0, v20, v0
	v_add_u32_e32 v0, 1, v0
	v_cvt_f32_i32_e32 v0, v0
	v_lshlrev_b32_e32 v24, 16, v16
	v_and_b32_e32 v25, 0xffff0000, v16
	v_lshlrev_b32_e32 v16, 16, v17
	v_and_b32_e32 v17, 0xffff0000, v17
	s_waitcnt vmcnt(4)
	v_cndmask_b32_e32 v40, 0, v238, vcc
	v_max_i32_e32 v10, 0, v50
	v_cndmask_b32_e32 v28, 0, v239, vcc
	v_cndmask_b32_e32 v29, 0, v240, vcc
	v_cndmask_b32_e32 v19, 0, v241, vcc
	v_add_u32_e32 v250, 7, v167
	v_max_i32_e32 v250, 0, v250
	v_min_u32_e32 v250, v250, v179
	v_mad_u64_u32 v[250:251], s[98:99], v250, s72, v[32:33]
	global_load_dwordx4 v[238:241], v[250:251], off
	v_cmp_lt_i32_e32 vcc, -4, v167
	v_min_u32_e32 v10, v10, v179
	s_and_b64 vcc, vcc, s[0:1]
	v_mad_u64_u32 v[10:11], s[0:1], v10, s72, v[32:33]
	v_cmp_lt_i32_e64 s[0:1], v56, v131
	v_and_b32_e32 v43, 0xffff0000, v40
	s_waitcnt vmcnt(4)
	v_cndmask_b32_e32 v48, 0, v242, vcc
	v_max_i32_e32 v10, 0, v56
	v_cndmask_b32_e32 v45, 0, v243, vcc
	v_cndmask_b32_e32 v49, 0, v244, vcc
	v_cndmask_b32_e32 v52, 0, v245, vcc
	v_cmp_lt_i32_e32 vcc, -5, v167
	v_min_u32_e32 v10, v10, v179
	s_and_b64 vcc, vcc, s[0:1]
	v_mad_u64_u32 v[10:11], s[0:1], v10, s72, v[32:33]
	v_cmp_lt_i32_e64 s[0:1], v35, v131
	s_waitcnt vmcnt(3)
	v_cndmask_b32_e32 v58, 0, v246, vcc
	v_max_i32_e32 v10, 0, v35
	v_cndmask_b32_e32 v54, 0, v247, vcc
	v_cndmask_b32_e32 v55, 0, v248, vcc
	v_cndmask_b32_e32 v51, 0, v249, vcc
	v_cmp_lt_i32_e32 vcc, -6, v167
	v_min_u32_e32 v10, v10, v179
	s_and_b64 vcc, vcc, s[0:1]
	v_mad_u64_u32 v[10:11], s[0:1], v10, s72, v[32:33]
	v_cmp_lt_i32_e64 s[0:1], v34, v131
	v_lshlrev_b32_e32 v74, 16, v58
	v_and_b32_e32 v75, 0xffff0000, v58
	v_min_i32_e32 v58, v35, v131
	v_max_i32_e32 v35, 1, v35
	s_waitcnt vmcnt(2)
	v_cndmask_b32_e32 v65, 0, v226, vcc
	v_max_i32_e32 v10, 0, v34
	v_cndmask_b32_e32 v64, 0, v227, vcc
	v_cndmask_b32_e32 v59, 0, v228, vcc
	v_cndmask_b32_e32 v57, 0, v229, vcc
	v_cmp_lt_i32_e32 vcc, -7, v167
	v_min_u32_e32 v10, v10, v179
	s_and_b64 vcc, vcc, s[0:1]
	v_mad_u64_u32 v[10:11], s[0:1], v10, s72, v[32:33]
	v_cmp_lt_i32_e64 s[0:1], v21, v131
	v_lshlrev_b32_e32 v76, 16, v65
	v_and_b32_e32 v77, 0xffff0000, v65
	v_lshlrev_b32_e32 v80, 16, v64
	v_and_b32_e32 v81, 0xffff0000, v64
	v_lshlrev_b32_e32 v64, 16, v59
	v_and_b32_e32 v65, 0xffff0000, v59
	v_min_i32_e32 v59, v34, v131
	v_sub_u32_e32 v35, v59, v35
	v_add_u32_e32 v35, 1, v35
	v_cvt_f32_i32_e32 v35, v35
	v_max_i32_e32 v34, 1, v34
	s_waitcnt vmcnt(1)
	v_cndmask_b32_e32 v53, 0, v230, vcc
	v_max_i32_e32 v10, 0, v21
	v_cndmask_b32_e32 v47, 0, v231, vcc
	v_cndmask_b32_e32 v37, 0, v232, vcc
	v_cndmask_b32_e32 v36, 0, v233, vcc
	v_cmp_lt_i32_e32 vcc, -8, v167
	v_min_u32_e32 v10, v10, v179
	s_and_b64 vcc, vcc, s[0:1]
	v_mad_u64_u32 v[10:11], s[0:1], v10, s72, v[32:33]
	v_div_scale_f32 v20, s[0:1], v0, v0, 1.0
	v_cmp_lt_i32_e64 s[0:1], v18, v131
	v_max_i32_e32 v18, 1, v18
	v_lshlrev_b32_e32 v92, 16, v37
	v_and_b32_e32 v93, 0xffff0000, v37
	v_lshlrev_b32_e32 v88, 16, v47
	v_and_b32_e32 v89, 0xffff0000, v47
	v_lshlrev_b32_e32 v84, 16, v53
	v_and_b32_e32 v85, 0xffff0000, v53
	s_waitcnt vmcnt(0)
	v_cndmask_b32_e32 v70, 0, v240, vcc
	v_cndmask_b32_e32 v67, 0, v241, vcc
	v_lshlrev_b32_e32 v12, 16, v26
	v_and_b32_e32 v13, 0xffff0000, v26
	v_rcp_f32_e32 v26, v20
	v_cndmask_b32_e32 v72, 0, v238, vcc
	v_cndmask_b32_e32 v71, 0, v239, vcc
	v_lshlrev_b32_e32 v10, 16, v6
	v_fma_f32 v27, -v20, v26, 1.0
	v_fmac_f32_e32 v26, v27, v26
	v_div_scale_f32 v27, vcc, 1.0, v0, 1.0
	v_mul_f32_e32 v32, v27, v26
	v_fma_f32 v33, -v20, v32, v27
	v_fmac_f32_e32 v32, v33, v26
	v_fma_f32 v20, -v20, v32, v27
	v_div_fmas_f32 v20, v20, v26, v32
	v_cmp_lt_i32_e32 vcc, -2, v167
	s_and_b64 vcc, vcc, s[0:1]
	v_div_fixup_f32 v0, v20, v0, 1.0
	v_cndmask_b32_e32 v20, 0, v237, vcc
	v_cndmask_b32_e32 v3, 0, v235, vcc
	v_cndmask_b32_e32 v2, 0, v234, vcc
	v_lshlrev_b32_e32 v38, 16, v2
	v_and_b32_e32 v39, 0xffff0000, v2
	v_lshlrev_b32_e32 v26, 16, v3
	v_and_b32_e32 v27, 0xffff0000, v3
	v_lshlrev_b32_e32 v2, 16, v20
	v_and_b32_e32 v3, 0xffff0000, v20
	v_min_i32_e32 v20, v44, v131
	v_sub_u32_e32 v18, v20, v18
	v_add_u32_e32 v18, 1, v18
	v_cvt_f32_i32_e32 v18, v18
	v_cndmask_b32_e32 v5, 0, v236, vcc
	v_div_scale_f32 v59, s[0:1], v35, v35, 1.0
	v_div_scale_f32 v20, s[0:1], v18, v18, 1.0
	v_rcp_f32_e32 v32, v20
	v_and_b32_e32 v11, 0xffff0000, v6
	v_lshlrev_b32_e32 v4, 16, v5
	v_and_b32_e32 v5, 0xffff0000, v5
	v_fma_f32 v33, -v20, v32, 1.0
	v_fmac_f32_e32 v32, v33, v32
	v_div_scale_f32 v33, vcc, 1.0, v18, 1.0
	v_mul_f32_e32 v41, v33, v32
	v_fma_f32 v42, -v20, v41, v33
	v_fmac_f32_e32 v41, v42, v32
	v_fma_f32 v20, -v20, v41, v33
	v_div_fmas_f32 v20, v20, v32, v41
	v_max_i32_e32 v32, 1, v44
	v_min_i32_e32 v33, v50, v131
	v_sub_u32_e32 v32, v33, v32
	v_add_u32_e32 v32, 1, v32
	v_cvt_f32_i32_e32 v32, v32
	v_max_i32_e32 v50, 1, v50
	v_lshlrev_b32_e32 v42, 16, v40
	v_div_fixup_f32 v20, v20, v18, 1.0
	v_div_scale_f32 v33, s[0:1], v32, v32, 1.0
	v_rcp_f32_e32 v44, v33
	v_lshlrev_b32_e32 v40, 16, v28
	v_and_b32_e32 v41, 0xffff0000, v28
	v_lshlrev_b32_e32 v28, 16, v29
	v_fma_f32 v46, -v33, v44, 1.0
	v_fmac_f32_e32 v44, v46, v44
	v_div_scale_f32 v46, vcc, 1.0, v32, 1.0
	v_mul_f32_e32 v60, v46, v44
	v_fma_f32 v61, -v33, v60, v46
	v_fmac_f32_e32 v60, v61, v44
	v_fma_f32 v33, -v33, v60, v46
	v_div_fmas_f32 v33, v33, v44, v60
	v_div_fixup_f32 v46, v33, v32, 1.0
	v_lshlrev_b32_e32 v32, 16, v52
	v_and_b32_e32 v33, 0xffff0000, v52
	v_min_i32_e32 v52, v56, v131
	v_sub_u32_e32 v50, v52, v50
	v_add_u32_e32 v50, 1, v50
	v_cvt_f32_i32_e32 v50, v50
	v_max_i32_e32 v56, 1, v56
	v_sub_u32_e32 v56, v58, v56
	v_add_u32_e32 v56, 1, v56
	v_div_scale_f32 v52, s[0:1], v50, v50, 1.0
	v_rcp_f32_e32 v62, v52
	v_cvt_f32_i32_e32 v56, v56
	v_lshlrev_b32_e32 v60, 16, v48
	v_and_b32_e32 v61, 0xffff0000, v48
	v_fma_f32 v63, -v52, v62, 1.0
	v_fmac_f32_e32 v62, v63, v62
	v_div_scale_f32 v63, vcc, 1.0, v50, 1.0
	v_mul_f32_e32 v66, v63, v62
	v_fma_f32 v68, -v52, v66, v63
	v_fmac_f32_e32 v66, v68, v62
	v_fma_f32 v52, -v52, v66, v63
	v_div_scale_f32 v58, s[0:1], v56, v56, 1.0
	v_div_fmas_f32 v52, v52, v62, v66
	v_rcp_f32_e32 v66, v58
	v_div_fixup_f32 v52, v52, v50, 1.0
	v_lshlrev_b32_e32 v44, 16, v45
	v_and_b32_e32 v45, 0xffff0000, v45
	v_fma_f32 v68, -v58, v66, 1.0
	v_fmac_f32_e32 v66, v68, v66
	v_div_scale_f32 v68, vcc, 1.0, v56, 1.0
	v_mul_f32_e32 v69, v68, v66
	v_fma_f32 v73, -v58, v69, v68
	v_fmac_f32_e32 v69, v73, v66
	v_fma_f32 v58, -v58, v69, v68
	v_div_fmas_f32 v58, v58, v66, v69
	v_rcp_f32_e32 v66, v59
	v_div_fixup_f32 v58, v58, v56, 1.0
	v_lshlrev_b32_e32 v62, 16, v54
	v_and_b32_e32 v63, 0xffff0000, v54
	v_fma_f32 v68, -v59, v66, 1.0
	v_fmac_f32_e32 v66, v68, v66
	v_div_scale_f32 v68, vcc, 1.0, v35, 1.0
	v_mul_f32_e32 v69, v68, v66
	v_fma_f32 v73, -v59, v69, v68
	v_fmac_f32_e32 v69, v73, v66
	v_fma_f32 v59, -v59, v69, v68
	v_div_fmas_f32 v59, v59, v66, v69
	v_div_fixup_f32 v66, v59, v35, 1.0
	v_min_i32_e32 v35, v21, v131
	v_sub_u32_e32 v34, v35, v34
	v_add_u32_e32 v34, 1, v34
	v_cvt_f32_i32_e32 v34, v34
	v_lshlrev_b32_e32 v68, 16, v36
	v_and_b32_e32 v69, 0xffff0000, v36
	v_and_b32_e32 v29, 0xffff0000, v29
	v_div_scale_f32 v35, s[0:1], v34, v34, 1.0
	v_rcp_f32_e32 v36, v35
	v_lshlrev_b32_e32 v48, 16, v49
	v_and_b32_e32 v49, 0xffff0000, v49
	v_lshlrev_b32_e32 v54, 16, v55
	v_fma_f32 v37, -v35, v36, 1.0
	v_fmac_f32_e32 v36, v37, v36
	v_div_scale_f32 v37, vcc, 1.0, v34, 1.0
	v_mul_f32_e32 v47, v37, v36
	v_fma_f32 v53, -v35, v47, v37
	v_fmac_f32_e32 v47, v53, v36
	v_fma_f32 v35, -v35, v47, v37
	v_div_fmas_f32 v35, v35, v36, v47
	v_div_fixup_f32 v94, v35, v34, 1.0
	v_lshlrev_b32_e32 v34, 16, v72
	v_and_b32_e32 v35, 0xffff0000, v72
	v_pk_add_f32 v[72:73], v[22:23], 0 op_sel_hi:[1,0]
	v_pk_add_f32 v[22:23], v[38:39], v[22:23] neg_lo:[0,1] neg_hi:[0,1]
	v_pk_add_f32 v[78:79], v[72:73], v[24:25]
	v_and_b32_e32 v55, 0xffff0000, v55
	v_pk_fma_f32 v[72:73], v[0:1], v[78:79], v[24:25] op_sel_hi:[0,1,1] neg_lo:[0,0,1] neg_hi:[0,0,1]
	v_pk_add_f32 v[78:79], v[78:79], v[22:23]
	v_pk_add_f32 v[24:25], v[42:43], v[24:25] neg_lo:[0,1] neg_hi:[0,1]
	v_pk_fma_f32 v[22:23], v[20:21], v[78:79], v[38:39] op_sel_hi:[0,1,1] neg_lo:[0,0,1] neg_hi:[0,0,1]
	v_pk_add_f32 v[24:25], v[78:79], v[24:25]
	v_pk_add_f32 v[38:39], v[60:61], v[38:39] neg_lo:[0,1] neg_hi:[0,1]
	v_pk_fma_f32 v[78:79], v[46:47], v[24:25], v[42:43] op_sel_hi:[0,1,1] neg_lo:[0,0,1] neg_hi:[0,0,1]
	v_pk_add_f32 v[24:25], v[24:25], v[38:39]
	v_cvt_pk_bf16_f32 v78, v78, v79
	v_pk_fma_f32 v[38:39], v[52:53], v[24:25], v[60:61] op_sel_hi:[0,1,1] neg_lo:[0,0,1] neg_hi:[0,0,1]
	v_cvt_pk_bf16_f32 v82, v38, v39
	v_pk_add_f32 v[38:39], v[74:75], v[42:43] neg_lo:[0,1] neg_hi:[0,1]
	v_lshlrev_b32_e32 v6, 16, v7
	v_pk_add_f32 v[24:25], v[24:25], v[38:39]
	v_and_b32_e32 v7, 0xffff0000, v7
	v_pk_fma_f32 v[38:39], v[58:59], v[24:25], v[74:75] op_sel_hi:[0,1,1] neg_lo:[0,0,1] neg_hi:[0,0,1]
	v_cvt_pk_bf16_f32 v86, v38, v39
	v_pk_add_f32 v[38:39], v[76:77], v[60:61] neg_lo:[0,1] neg_hi:[0,1]
	v_lshlrev_b32_e32 v18, 16, v19
	v_pk_add_f32 v[24:25], v[24:25], v[38:39]
	v_and_b32_e32 v19, 0xffff0000, v19
	v_pk_fma_f32 v[38:39], v[66:67], v[24:25], v[76:77] op_sel_hi:[0,1,1] neg_lo:[0,0,1] neg_hi:[0,0,1]
	v_cvt_pk_bf16_f32 v60, v38, v39
	v_pk_add_f32 v[38:39], v[84:85], v[74:75] neg_lo:[0,1] neg_hi:[0,1]
	v_cvt_pk_bf16_f32 v22, v22, v23
	v_pk_add_f32 v[24:25], v[24:25], v[38:39]
	v_lshlrev_b32_e32 v50, 16, v51
	v_pk_fma_f32 v[38:39], v[94:95], v[24:25], v[84:85] op_sel_hi:[0,1,1] neg_lo:[0,0,1] neg_hi:[0,0,1]
	v_cvt_pk_bf16_f32 v90, v38, v39
	v_pk_add_f32 v[38:39], v[34:35], v[76:77] neg_lo:[0,1] neg_hi:[0,1]
	v_and_b32_e32 v51, 0xffff0000, v51
	v_pk_add_f32 v[42:43], v[24:25], v[38:39]
	v_pk_add_f32 v[24:25], v[14:15], 0 op_sel_hi:[1,0]
	v_pk_add_f32 v[14:15], v[26:27], v[14:15] neg_lo:[0,1] neg_hi:[0,1]
	v_pk_add_f32 v[24:25], v[24:25], v[16:17]
	v_lshlrev_b32_e32 v38, 16, v71
	v_pk_fma_f32 v[74:75], v[0:1], v[24:25], v[16:17] op_sel_hi:[0,1,1] neg_lo:[0,0,1] neg_hi:[0,0,1]
	v_pk_add_f32 v[14:15], v[24:25], v[14:15]
	v_pk_add_f32 v[16:17], v[40:41], v[16:17] neg_lo:[0,1] neg_hi:[0,1]
	v_pk_fma_f32 v[24:25], v[20:21], v[14:15], v[26:27] op_sel_hi:[0,1,1] neg_lo:[0,0,1] neg_hi:[0,0,1]
	v_pk_add_f32 v[14:15], v[14:15], v[16:17]
	v_and_b32_e32 v39, 0xffff0000, v71
	v_pk_fma_f32 v[16:17], v[46:47], v[14:15], v[40:41] op_sel_hi:[0,1,1] neg_lo:[0,0,1] neg_hi:[0,0,1]
	v_cvt_pk_bf16_f32 v79, v16, v17
	v_pk_add_f32 v[16:17], v[44:45], v[26:27] neg_lo:[0,1] neg_hi:[0,1]
	v_cvt_pk_bf16_f32 v23, v24, v25
	v_pk_add_f32 v[14:15], v[14:15], v[16:17]
	v_lshlrev_b32_e32 v56, 16, v57
	v_pk_fma_f32 v[16:17], v[52:53], v[14:15], v[44:45] op_sel_hi:[0,1,1] neg_lo:[0,0,1] neg_hi:[0,0,1]
	v_cvt_pk_bf16_f32 v83, v16, v17
	v_pk_add_f32 v[16:17], v[62:63], v[40:41] neg_lo:[0,1] neg_hi:[0,1]
	v_lshlrev_b32_e32 v40, 16, v70
	v_pk_add_f32 v[14:15], v[14:15], v[16:17]
	v_and_b32_e32 v41, 0xffff0000, v70
	v_pk_fma_f32 v[16:17], v[58:59], v[14:15], v[62:63] op_sel_hi:[0,1,1] neg_lo:[0,0,1] neg_hi:[0,0,1]
	v_cvt_pk_bf16_f32 v87, v16, v17
	v_pk_add_f32 v[16:17], v[80:81], v[44:45] neg_lo:[0,1] neg_hi:[0,1]
	v_and_b32_e32 v57, 0xffff0000, v57
	v_pk_add_f32 v[14:15], v[14:15], v[16:17]
	v_and_b32_e32 v37, 0xffff0000, v67
	v_pk_fma_f32 v[16:17], v[66:67], v[14:15], v[80:81] op_sel_hi:[0,1,1] neg_lo:[0,0,1] neg_hi:[0,0,1]
	v_cvt_pk_bf16_f32 v61, v16, v17
	v_pk_add_f32 v[16:17], v[88:89], v[62:63] neg_lo:[0,1] neg_hi:[0,1]
	v_lshlrev_b32_e32 v36, 16, v67
	v_pk_add_f32 v[14:15], v[14:15], v[16:17]
	v_cvt_pk_bf16_f32 v72, v72, v73
	v_pk_fma_f32 v[16:17], v[94:95], v[14:15], v[88:89] op_sel_hi:[0,1,1] neg_lo:[0,0,1] neg_hi:[0,0,1]
	v_cvt_pk_bf16_f32 v91, v16, v17
	v_pk_add_f32 v[16:17], v[38:39], v[80:81] neg_lo:[0,1] neg_hi:[0,1]
	v_cvt_pk_bf16_f32 v73, v74, v75
	v_pk_add_f32 v[44:45], v[14:15], v[16:17]
	v_pk_add_f32 v[14:15], v[10:11], 0 op_sel_hi:[1,0]
	v_pk_add_f32 v[10:11], v[4:5], v[10:11] neg_lo:[0,1] neg_hi:[0,1]
	v_pk_add_f32 v[14:15], v[14:15], v[12:13]
	s_nop 0
	v_pk_fma_f32 v[16:17], v[0:1], v[14:15], v[12:13] op_sel_hi:[0,1,1] neg_lo:[0,0,1] neg_hi:[0,0,1]
	v_pk_add_f32 v[10:11], v[14:15], v[10:11]
	v_pk_add_f32 v[12:13], v[28:29], v[12:13] neg_lo:[0,1] neg_hi:[0,1]
	v_pk_fma_f32 v[14:15], v[20:21], v[10:11], v[4:5] op_sel_hi:[0,1,1] neg_lo:[0,0,1] neg_hi:[0,0,1]
	v_pk_add_f32 v[10:11], v[10:11], v[12:13]
	v_pk_add_f32 v[4:5], v[48:49], v[4:5] neg_lo:[0,1] neg_hi:[0,1]
	v_pk_fma_f32 v[12:13], v[46:47], v[10:11], v[28:29] op_sel_hi:[0,1,1] neg_lo:[0,0,1] neg_hi:[0,0,1]
	v_pk_add_f32 v[4:5], v[10:11], v[4:5]
	v_cvt_pk_bf16_f32 v74, v16, v17
	v_pk_fma_f32 v[10:11], v[52:53], v[4:5], v[48:49] op_sel_hi:[0,1,1] neg_lo:[0,0,1] neg_hi:[0,0,1]
	v_cvt_pk_bf16_f32 v84, v10, v11
	v_pk_add_f32 v[10:11], v[54:55], v[28:29] neg_lo:[0,1] neg_hi:[0,1]
	v_cvt_pk_bf16_f32 v24, v14, v15
	v_pk_add_f32 v[4:5], v[4:5], v[10:11]
	v_cvt_pk_bf16_f32 v80, v12, v13
	v_pk_fma_f32 v[10:11], v[58:59], v[4:5], v[54:55] op_sel_hi:[0,1,1] neg_lo:[0,0,1] neg_hi:[0,0,1]
	v_cvt_pk_bf16_f32 v88, v10, v11
	v_pk_add_f32 v[10:11], v[64:65], v[48:49] neg_lo:[0,1] neg_hi:[0,1]
	s_nop 0
	v_pk_add_f32 v[4:5], v[4:5], v[10:11]
	s_nop 0
	v_pk_fma_f32 v[10:11], v[66:67], v[4:5], v[64:65] op_sel_hi:[0,1,1] neg_lo:[0,0,1] neg_hi:[0,0,1]
	v_cvt_pk_bf16_f32 v62, v10, v11
	v_pk_add_f32 v[10:11], v[92:93], v[54:55] neg_lo:[0,1] neg_hi:[0,1]
	s_nop 0
	v_pk_add_f32 v[4:5], v[4:5], v[10:11]
	s_nop 0
	v_pk_fma_f32 v[10:11], v[94:95], v[4:5], v[92:93] op_sel_hi:[0,1,1] neg_lo:[0,0,1] neg_hi:[0,0,1]
	v_cvt_pk_bf16_f32 v92, v10, v11
	v_pk_add_f32 v[10:11], v[40:41], v[64:65] neg_lo:[0,1] neg_hi:[0,1]
	s_nop 0
	v_pk_add_f32 v[76:77], v[4:5], v[10:11]
	v_pk_add_f32 v[4:5], v[6:7], 0 op_sel_hi:[1,0]
	v_pk_add_f32 v[6:7], v[2:3], v[6:7] neg_lo:[0,1] neg_hi:[0,1]
	v_pk_add_f32 v[4:5], v[4:5], v[8:9]
	s_nop 0
	v_pk_fma_f32 v[10:11], v[0:1], v[4:5], v[8:9] op_sel_hi:[0,1,1] neg_lo:[0,0,1] neg_hi:[0,0,1]
	v_pk_add_f32 v[4:5], v[4:5], v[6:7]
	v_cvt_pk_bf16_f32 v75, v10, v11
	v_pk_fma_f32 v[6:7], v[20:21], v[4:5], v[2:3] op_sel_hi:[0,1,1] neg_lo:[0,0,1] neg_hi:[0,0,1]
	v_cvt_pk_bf16_f32 v25, v6, v7
	v_pk_add_f32 v[6:7], v[18:19], v[8:9] neg_lo:[0,1] neg_hi:[0,1]
	v_pk_add_f32 v[2:3], v[32:33], v[2:3] neg_lo:[0,1] neg_hi:[0,1]
	v_pk_add_f32 v[4:5], v[4:5], v[6:7]
	v_max_i32_e32 v0, 1, v21
	v_pk_add_f32 v[2:3], v[4:5], v[2:3]
	v_pk_fma_f32 v[6:7], v[46:47], v[4:5], v[18:19] op_sel_hi:[0,1,1] neg_lo:[0,0,1] neg_hi:[0,0,1]
	v_pk_fma_f32 v[4:5], v[52:53], v[2:3], v[32:33] op_sel_hi:[0,1,1] neg_lo:[0,0,1] neg_hi:[0,0,1]
	v_cvt_pk_bf16_f32 v85, v4, v5
	v_pk_add_f32 v[4:5], v[50:51], v[18:19] neg_lo:[0,1] neg_hi:[0,1]
	v_cvt_pk_bf16_f32 v81, v6, v7
	v_pk_add_f32 v[2:3], v[2:3], v[4:5]
	v_add_co_u32_e32 v6, vcc, s87, v30
	v_pk_fma_f32 v[4:5], v[58:59], v[2:3], v[50:51] op_sel_hi:[0,1,1] neg_lo:[0,0,1] neg_hi:[0,0,1]
	v_cvt_pk_bf16_f32 v89, v4, v5
	v_pk_add_f32 v[4:5], v[56:57], v[32:33] neg_lo:[0,1] neg_hi:[0,1]
	v_addc_co_u32_e32 v7, vcc, 0, v31, vcc
	v_pk_add_f32 v[2:3], v[2:3], v[4:5]
	global_store_dwordx4 v[30:31], v[72:75], off
	global_store_dwordx4 v[30:31], v[22:25], off offset:1024
	global_store_dwordx4 v[30:31], v[78:81], off offset:2048
	global_store_dwordx4 v[30:31], v[82:85], off offset:3072
	v_pk_fma_f32 v[4:5], v[66:67], v[2:3], v[56:57] op_sel_hi:[0,1,1] neg_lo:[0,0,1] neg_hi:[0,0,1]
	v_cvt_pk_bf16_f32 v63, v4, v5
	v_pk_add_f32 v[4:5], v[68:69], v[50:51] neg_lo:[0,1] neg_hi:[0,1]
	s_nop 0
	v_pk_add_f32 v[2:3], v[2:3], v[4:5]
	s_nop 0
	v_pk_fma_f32 v[4:5], v[94:95], v[2:3], v[68:69] op_sel_hi:[0,1,1] neg_lo:[0,0,1] neg_hi:[0,0,1]
	v_cvt_pk_bf16_f32 v93, v4, v5
	v_pk_add_f32 v[4:5], v[36:37], v[56:57] neg_lo:[0,1] neg_hi:[0,1]
	global_store_dwordx4 v[6:7], v[86:89], off
	global_store_dwordx4 v[6:7], v[60:63], off offset:1024
	global_store_dwordx4 v[6:7], v[90:93], off offset:2048
	v_pk_add_f32 v[2:3], v[2:3], v[4:5]
	v_mov_b32_e32 v4, 1
	v_mov_b32_e32 v5, 8
